# peel first K iteration of every GEMM loop (SrcC=0 on first touch), accumulator zeroing off the loop path
# speedup vs baseline: 1.0185x; 1.0080x over previous
.LBB0_310:
	s_ashr_i32 s39, s38, 31
	s_lshl_b64 s[40:41], s[38:39], 19
	s_add_u32 s40, s16, s40
	s_addc_u32 s41, s17, s41
	s_ashr_i32 s37, s36, 31
	s_lshl_b64 s[42:43], s[36:37], 19
	s_add_u32 s42, s18, s42
	v_cmp_lt_i64_e64 s[6:7], s[6:7], v[140:141]
	s_addc_u32 s43, s19, s43
	s_andn2_b64 vcc, exec, s[24:25]
	s_cbranch_vccz .Lpz_P2b
	v_mov_b32_e32 v103, 0
	v_mov_b32_e32 v102, v103
	v_mov_b32_e32 v101, v103
	v_mov_b32_e32 v100, v103
	v_mov_b32_e32 v91, v103
	v_mov_b32_e32 v90, v103
	v_mov_b32_e32 v89, v103
	v_mov_b32_e32 v88, v103
	v_mov_b32_e32 v99, v103
	v_mov_b32_e32 v98, v103
	v_mov_b32_e32 v97, v103
	v_mov_b32_e32 v96, v103
	v_mov_b32_e32 v83, v103
	v_mov_b32_e32 v82, v103
	v_mov_b32_e32 v81, v103
	v_mov_b32_e32 v80, v103
	v_mov_b32_e32 v75, v103
	v_mov_b32_e32 v74, v103
	v_mov_b32_e32 v73, v103
	v_mov_b32_e32 v72, v103
	v_mov_b32_e32 v63, v103
	v_mov_b32_e32 v62, v103
	v_mov_b32_e32 v61, v103
	v_mov_b32_e32 v60, v103
	v_mov_b32_e32 v59, v103
	v_mov_b32_e32 v58, v103
	v_mov_b32_e32 v57, v103
	v_mov_b32_e32 v56, v103
	v_mov_b32_e32 v51, v103
	v_mov_b32_e32 v50, v103
	v_mov_b32_e32 v49, v103
	v_mov_b32_e32 v48, v103
	v_mov_b32_e32 v95, v103
	v_mov_b32_e32 v94, v103
	v_mov_b32_e32 v93, v103
	v_mov_b32_e32 v92, v103
	v_mov_b32_e32 v111, v103
	v_mov_b32_e32 v110, v103
	v_mov_b32_e32 v109, v103
	v_mov_b32_e32 v108, v103
	v_mov_b32_e32 v87, v103
	v_mov_b32_e32 v86, v103
	v_mov_b32_e32 v85, v103
	v_mov_b32_e32 v84, v103
	v_mov_b32_e32 v107, v103
	v_mov_b32_e32 v106, v103
	v_mov_b32_e32 v105, v103
	v_mov_b32_e32 v104, v103
	v_mov_b32_e32 v67, v103
	v_mov_b32_e32 v66, v103
	v_mov_b32_e32 v65, v103
	v_mov_b32_e32 v64, v103
	v_mov_b32_e32 v79, v103
	v_mov_b32_e32 v78, v103
	v_mov_b32_e32 v77, v103
	v_mov_b32_e32 v76, v103
	v_mov_b32_e32 v55, v103
	v_mov_b32_e32 v54, v103
	v_mov_b32_e32 v53, v103
	v_mov_b32_e32 v52, v103
	v_mov_b32_e32 v71, v103
	v_mov_b32_e32 v70, v103
	v_mov_b32_e32 v69, v103
	v_mov_b32_e32 v68, v103
	v_mov_b32_e32 v43, v103
	v_mov_b32_e32 v42, v103
	v_mov_b32_e32 v41, v103
	v_mov_b32_e32 v40, v103
	v_mov_b32_e32 v35, v103
	v_mov_b32_e32 v34, v103
	v_mov_b32_e32 v33, v103
	v_mov_b32_e32 v32, v103
	v_mov_b32_e32 v27, v103
	v_mov_b32_e32 v26, v103
	v_mov_b32_e32 v25, v103
	v_mov_b32_e32 v24, v103
	v_mov_b32_e32 v23, v103
	v_mov_b32_e32 v22, v103
	v_mov_b32_e32 v21, v103
	v_mov_b32_e32 v20, v103
	v_mov_b32_e32 v7, v103
	v_mov_b32_e32 v6, v103
	v_mov_b32_e32 v5, v103
	v_mov_b32_e32 v4, v103
	v_mov_b32_e32 v127, v103
	v_mov_b32_e32 v126, v103
	v_mov_b32_e32 v125, v103
	v_mov_b32_e32 v124, v103
	v_mov_b32_e32 v3, v103
	v_mov_b32_e32 v2, v103
	v_mov_b32_e32 v1, v103
	v_mov_b32_e32 v0, v103
	v_mov_b32_e32 v119, v103
	v_mov_b32_e32 v118, v103
	v_mov_b32_e32 v117, v103
	v_mov_b32_e32 v116, v103
	v_mov_b32_e32 v31, v103
	v_mov_b32_e32 v30, v103
	v_mov_b32_e32 v29, v103
	v_mov_b32_e32 v28, v103
	v_mov_b32_e32 v47, v103
	v_mov_b32_e32 v46, v103
	v_mov_b32_e32 v45, v103
	v_mov_b32_e32 v44, v103
	v_mov_b32_e32 v19, v103
	v_mov_b32_e32 v18, v103
	v_mov_b32_e32 v17, v103
	v_mov_b32_e32 v16, v103
	v_mov_b32_e32 v39, v103
	v_mov_b32_e32 v38, v103
	v_mov_b32_e32 v37, v103
	v_mov_b32_e32 v36, v103
	v_mov_b32_e32 v123, v103
	v_mov_b32_e32 v122, v103
	v_mov_b32_e32 v121, v103
	v_mov_b32_e32 v120, v103
	v_mov_b32_e32 v15, v103
	v_mov_b32_e32 v14, v103
	v_mov_b32_e32 v13, v103
	v_mov_b32_e32 v12, v103
	v_mov_b32_e32 v115, v103
	v_mov_b32_e32 v114, v103
	v_mov_b32_e32 v113, v103
	v_mov_b32_e32 v112, v103
	v_mov_b32_e32 v11, v103
	v_mov_b32_e32 v10, v103
	v_mov_b32_e32 v9, v103
	v_mov_b32_e32 v8, v103
	s_cbranch_vccnz .LBB0_313
.Lpz_P2b:
	s_and_b64 s[6:7], s[6:7], exec
	s_cselect_b32 s37, s41, s45
	s_cselect_b32 s39, s40, s44
	s_cselect_b32 s51, s43, s47
	s_cselect_b32 s65, s42, s46
	s_add_u32 s66, s46, 0x100
	s_addc_u32 s67, s47, 0
	s_mov_b32 s46, 0
	ds_read_b128 v[144:147], v166
	ds_read_b128 v[148:151], v166 offset:1024
	ds_read_b128 v[152:155], v166 offset:2048
	ds_read_b128 v[156:159], v166 offset:3072
	s_add_i32 s68, s46, 2
	s_add_u32 s6, s44, 0x100
	s_addc_u32 s7, s45, 0
	s_cmp_eq_u32 s60, s46
	s_cselect_b32 s46, s65, s66
	s_cselect_b32 s49, s37, s7
	s_cselect_b32 s48, s39, s6
	s_cselect_b32 s47, s51, s67
	v_lshl_add_u64 v[160:161], s[44:45], 0, v[136:137]
	s_add_i32 m0, s35, 0xc000
	ds_read_b128 v[170:173], v167
	ds_read_b128 v[174:177], v167 offset:1024
	ds_read_b128 v[178:181], v167 offset:2048
	ds_read_b128 v[182:185], v167 offset:3072
	ds_read_b128 v[186:189], v167 offset:4096
	ds_read_b128 v[190:193], v167 offset:5120
	ds_read_b128 v[194:197], v167 offset:6144
	ds_read_b128 v[198:201], v167 offset:7168
	global_load_lds_dwordx4 v[160:161], off
	v_lshl_add_u64 v[160:161], s[44:45], 0, v[138:139]
	s_add_i32 m0, s35, 0xe000
	s_nop 0
	global_load_lds_dwordx4 v[160:161], off
	s_waitcnt lgkmcnt(8)
	s_barrier
	s_waitcnt lgkmcnt(0)
	s_setprio 1
	s_waitcnt lgkmcnt(0)
	v_mfma_f32_16x16x32_bf16 v[100:103], v[144:147], v[170:173], 0
	v_mfma_f32_16x16x32_bf16 v[88:91], v[152:155], v[170:173], 0
	v_mfma_f32_16x16x32_bf16 v[96:99], v[144:147], v[178:181], 0
	v_mfma_f32_16x16x32_bf16 v[80:83], v[152:155], v[178:181], 0
	v_mfma_f32_16x16x32_bf16 v[72:75], v[144:147], v[186:189], 0
	v_mfma_f32_16x16x32_bf16 v[60:63], v[152:155], v[186:189], 0
	v_mfma_f32_16x16x32_bf16 v[56:59], v[144:147], v[194:197], 0
	v_mfma_f32_16x16x32_bf16 v[48:51], v[152:155], v[194:197], 0
	v_mfma_f32_16x16x32_bf16 v[100:103], v[148:151], v[174:177], v[100:103]
	v_mfma_f32_16x16x32_bf16 v[88:91], v[156:159], v[174:177], v[88:91]
	v_mfma_f32_16x16x32_bf16 v[96:99], v[148:151], v[182:185], v[96:99]
	v_mfma_f32_16x16x32_bf16 v[80:83], v[156:159], v[182:185], v[80:83]
	v_mfma_f32_16x16x32_bf16 v[72:75], v[148:151], v[190:193], v[72:75]
	v_mfma_f32_16x16x32_bf16 v[60:63], v[156:159], v[190:193], v[60:63]
	v_mfma_f32_16x16x32_bf16 v[56:59], v[148:151], v[198:201], v[56:59]
	v_mfma_f32_16x16x32_bf16 v[48:51], v[156:159], v[198:201], v[48:51]
	s_setprio 0
	s_barrier
	s_add_i32 s44, s62, s52
	v_lshl_add_u64 v[160:161], s[46:47], 0, v[132:133]
	s_mov_b32 m0, s44
	ds_read_b128 v[202:205], v168
	ds_read_b128 v[206:209], v168 offset:1024
	ds_read_b128 v[210:213], v168 offset:2048
	ds_read_b128 v[214:217], v168 offset:3072
	global_load_lds_dwordx4 v[160:161], off
	v_lshl_add_u64 v[218:219], s[46:47], 0, v[128:129]
	s_add_i32 m0, s44, 0x2000
	s_nop 0
	global_load_lds_dwordx4 v[218:219], off
	s_barrier
	s_waitcnt lgkmcnt(0)
	s_setprio 1
	s_waitcnt lgkmcnt(0)
	v_mfma_f32_16x16x32_bf16 v[92:95], v[202:205], v[170:173], 0
	v_mfma_f32_16x16x32_bf16 v[108:111], v[210:213], v[170:173], 0
	v_mfma_f32_16x16x32_bf16 v[84:87], v[202:205], v[178:181], 0
	v_mfma_f32_16x16x32_bf16 v[104:107], v[210:213], v[178:181], 0
	v_mfma_f32_16x16x32_bf16 v[64:67], v[202:205], v[186:189], 0
	v_mfma_f32_16x16x32_bf16 v[76:79], v[210:213], v[186:189], 0
	v_mfma_f32_16x16x32_bf16 v[52:55], v[202:205], v[194:197], 0
	v_mfma_f32_16x16x32_bf16 v[68:71], v[210:213], v[194:197], 0
	v_mfma_f32_16x16x32_bf16 v[92:95], v[206:209], v[174:177], v[92:95]
	v_mfma_f32_16x16x32_bf16 v[108:111], v[214:217], v[174:177], v[108:111]
	v_mfma_f32_16x16x32_bf16 v[84:87], v[206:209], v[182:185], v[84:87]
	v_mfma_f32_16x16x32_bf16 v[104:107], v[214:217], v[182:185], v[104:107]
	v_mfma_f32_16x16x32_bf16 v[64:67], v[206:209], v[190:193], v[64:67]
	v_mfma_f32_16x16x32_bf16 v[76:79], v[214:217], v[190:193], v[76:79]
	v_mfma_f32_16x16x32_bf16 v[52:55], v[206:209], v[198:201], v[52:55]
	v_mfma_f32_16x16x32_bf16 v[68:71], v[214:217], v[198:201], v[68:71]
	s_setprio 0
	s_mov_b32 m0, s35
	v_lshl_add_u64 v[220:221], s[48:49], 0, v[134:135]
	s_barrier
	ds_read_b128 v[170:173], v167 offset:16384
	ds_read_b128 v[174:177], v167 offset:17408
	ds_read_b128 v[178:181], v167 offset:18432
	ds_read_b128 v[182:185], v167 offset:19456
	ds_read_b128 v[186:189], v167 offset:20480
	ds_read_b128 v[190:193], v167 offset:21504
	ds_read_b128 v[194:197], v167 offset:22528
	ds_read_b128 v[198:201], v167 offset:23552
	global_load_lds_dwordx4 v[220:221], off
	v_lshl_add_u64 v[224:225], s[48:49], 0, v[130:131]
	s_mov_b32 m0, s53
	s_nop 0
	global_load_lds_dwordx4 v[224:225], off
	s_barrier
	s_waitcnt lgkmcnt(0)
	s_setprio 1
	s_waitcnt lgkmcnt(0)
	v_mfma_f32_16x16x32_bf16 v[40:43], v[144:147], v[170:173], 0
	v_mfma_f32_16x16x32_bf16 v[32:35], v[152:155], v[170:173], 0
	v_mfma_f32_16x16x32_bf16 v[24:27], v[144:147], v[178:181], 0
	v_mfma_f32_16x16x32_bf16 v[20:23], v[152:155], v[178:181], 0
	v_mfma_f32_16x16x32_bf16 v[4:7], v[144:147], v[186:189], 0
	v_mfma_f32_16x16x32_bf16 v[124:127], v[152:155], v[186:189], 0
	v_mfma_f32_16x16x32_bf16 v[0:3], v[144:147], v[194:197], 0
	v_mfma_f32_16x16x32_bf16 v[116:119], v[152:155], v[194:197], 0
	v_mfma_f32_16x16x32_bf16 v[40:43], v[148:151], v[174:177], v[40:43]
	v_mfma_f32_16x16x32_bf16 v[32:35], v[156:159], v[174:177], v[32:35]
	v_mfma_f32_16x16x32_bf16 v[24:27], v[148:151], v[182:185], v[24:27]
	v_mfma_f32_16x16x32_bf16 v[20:23], v[156:159], v[182:185], v[20:23]
	v_mfma_f32_16x16x32_bf16 v[4:7], v[148:151], v[190:193], v[4:7]
	v_mfma_f32_16x16x32_bf16 v[124:127], v[156:159], v[190:193], v[124:127]
	v_mfma_f32_16x16x32_bf16 v[0:3], v[148:151], v[198:201], v[0:3]
	v_mfma_f32_16x16x32_bf16 v[116:119], v[156:159], v[198:201], v[116:119]
	s_setprio 0
	s_barrier
	s_add_u32 s44, s46, 0x40000
	s_addc_u32 s45, s47, 0
	s_add_i32 s69, s64, s52
	v_lshl_add_u64 v[144:145], s[44:45], 0, v[132:133]
	s_mov_b32 m0, s69
	s_nop 0
	global_load_lds_dwordx4 v[144:145], off
	v_lshl_add_u64 v[144:145], s[44:45], 0, v[128:129]
	s_add_i32 m0, s69, 0x2000
	s_nop 0
	global_load_lds_dwordx4 v[144:145], off
	s_waitcnt vmcnt(6)
	s_barrier
	s_setprio 1
	v_mfma_f32_16x16x32_bf16 v[28:31], v[202:205], v[170:173], 0
	v_mfma_f32_16x16x32_bf16 v[44:47], v[210:213], v[170:173], 0
	v_mfma_f32_16x16x32_bf16 v[16:19], v[202:205], v[178:181], 0
	v_mfma_f32_16x16x32_bf16 v[36:39], v[210:213], v[178:181], 0
	v_mfma_f32_16x16x32_bf16 v[120:123], v[202:205], v[186:189], 0
	v_mfma_f32_16x16x32_bf16 v[12:15], v[210:213], v[186:189], 0
	v_mfma_f32_16x16x32_bf16 v[112:115], v[202:205], v[194:197], 0
	v_mfma_f32_16x16x32_bf16 v[8:11], v[210:213], v[194:197], 0
	v_mfma_f32_16x16x32_bf16 v[28:31], v[206:209], v[174:177], v[28:31]
	v_mfma_f32_16x16x32_bf16 v[44:47], v[214:217], v[174:177], v[44:47]
	v_mfma_f32_16x16x32_bf16 v[16:19], v[206:209], v[182:185], v[16:19]
	v_mfma_f32_16x16x32_bf16 v[36:39], v[214:217], v[182:185], v[36:39]
	v_mfma_f32_16x16x32_bf16 v[120:123], v[206:209], v[190:193], v[120:123]
	v_mfma_f32_16x16x32_bf16 v[12:15], v[214:217], v[190:193], v[12:15]
	v_mfma_f32_16x16x32_bf16 v[112:115], v[206:209], v[198:201], v[112:115]
	v_mfma_f32_16x16x32_bf16 v[8:11], v[214:217], v[198:201], v[8:11]
	s_setprio 0
	s_add_i32 s69, 0, 0x18000
	v_add_u32_e32 v156, s69, v163
	s_barrier
	ds_read_b128 v[144:147], v156
	ds_read_b128 v[148:151], v156 offset:1024
	ds_read_b128 v[152:155], v156 offset:2048
	ds_read_b128 v[156:159], v156 offset:3072
	s_add_u32 s44, s48, 0x2000
	s_addc_u32 s45, s49, 0
	s_mov_b32 m0, s54
	v_lshl_add_u64 v[202:203], s[44:45], 0, v[134:135]
	ds_read_b128 v[170:173], v167 offset:32768
	ds_read_b128 v[174:177], v167 offset:33792
	ds_read_b128 v[178:181], v167 offset:34816
	ds_read_b128 v[182:185], v167 offset:35840
	ds_read_b128 v[186:189], v167 offset:36864
	ds_read_b128 v[190:193], v167 offset:37888
	ds_read_b128 v[194:197], v167 offset:38912
	ds_read_b128 v[198:201], v167 offset:39936
	global_load_lds_dwordx4 v[202:203], off
	v_lshl_add_u64 v[202:203], s[44:45], 0, v[130:131]
	s_mov_b32 m0, s55
	s_nop 0
	global_load_lds_dwordx4 v[202:203], off
	s_waitcnt lgkmcnt(8)
	s_barrier
	s_waitcnt lgkmcnt(0)
	s_setprio 1
	s_waitcnt lgkmcnt(0)
	v_mfma_f32_16x16x32_bf16 v[100:103], v[144:147], v[170:173], v[100:103]
	v_mfma_f32_16x16x32_bf16 v[88:91], v[152:155], v[170:173], v[88:91]
	v_mfma_f32_16x16x32_bf16 v[96:99], v[144:147], v[178:181], v[96:99]
	v_mfma_f32_16x16x32_bf16 v[80:83], v[152:155], v[178:181], v[80:83]
	v_mfma_f32_16x16x32_bf16 v[72:75], v[144:147], v[186:189], v[72:75]
	v_mfma_f32_16x16x32_bf16 v[60:63], v[152:155], v[186:189], v[60:63]
	v_mfma_f32_16x16x32_bf16 v[56:59], v[144:147], v[194:197], v[56:59]
	v_mfma_f32_16x16x32_bf16 v[48:51], v[152:155], v[194:197], v[48:51]
	v_mfma_f32_16x16x32_bf16 v[100:103], v[148:151], v[174:177], v[100:103]
	v_mfma_f32_16x16x32_bf16 v[88:91], v[156:159], v[174:177], v[88:91]
	v_mfma_f32_16x16x32_bf16 v[96:99], v[148:151], v[182:185], v[96:99]
	v_mfma_f32_16x16x32_bf16 v[80:83], v[156:159], v[182:185], v[80:83]
	v_mfma_f32_16x16x32_bf16 v[72:75], v[148:151], v[190:193], v[72:75]
	v_mfma_f32_16x16x32_bf16 v[60:63], v[156:159], v[190:193], v[60:63]
	v_mfma_f32_16x16x32_bf16 v[56:59], v[148:151], v[198:201], v[56:59]
	v_mfma_f32_16x16x32_bf16 v[48:51], v[156:159], v[198:201], v[48:51]
	s_setprio 0
	s_barrier
	s_add_i32 s48, 0, 0x1c000
	s_add_i32 s44, s69, s52
	v_add_u32_e32 v169, s48, v163
	v_lshl_add_u64 v[160:161], v[160:161], 0, s[20:21]
	s_mov_b32 m0, s44
	ds_read_b128 v[202:205], v169
	ds_read_b128 v[206:209], v169 offset:1024
	ds_read_b128 v[210:213], v169 offset:2048
	ds_read_b128 v[214:217], v169 offset:3072
	global_load_lds_dwordx4 v[160:161], off
	v_lshl_add_u64 v[160:161], v[218:219], 0, s[20:21]
	s_add_i32 m0, s44, 0x2000
	s_nop 0
	global_load_lds_dwordx4 v[160:161], off
	s_barrier
	s_waitcnt lgkmcnt(0)
	s_setprio 1
	s_waitcnt lgkmcnt(0)
	v_mfma_f32_16x16x32_bf16 v[92:95], v[202:205], v[170:173], v[92:95]
	v_mfma_f32_16x16x32_bf16 v[108:111], v[210:213], v[170:173], v[108:111]
	v_mfma_f32_16x16x32_bf16 v[84:87], v[202:205], v[178:181], v[84:87]
	v_mfma_f32_16x16x32_bf16 v[104:107], v[210:213], v[178:181], v[104:107]
	v_mfma_f32_16x16x32_bf16 v[64:67], v[202:205], v[186:189], v[64:67]
	v_mfma_f32_16x16x32_bf16 v[76:79], v[210:213], v[186:189], v[76:79]
	v_mfma_f32_16x16x32_bf16 v[52:55], v[202:205], v[194:197], v[52:55]
	v_mfma_f32_16x16x32_bf16 v[68:71], v[210:213], v[194:197], v[68:71]
	v_mfma_f32_16x16x32_bf16 v[92:95], v[206:209], v[174:177], v[92:95]
	v_mfma_f32_16x16x32_bf16 v[108:111], v[214:217], v[174:177], v[108:111]
	v_mfma_f32_16x16x32_bf16 v[84:87], v[206:209], v[182:185], v[84:87]
	v_mfma_f32_16x16x32_bf16 v[104:107], v[214:217], v[182:185], v[104:107]
	v_mfma_f32_16x16x32_bf16 v[64:67], v[206:209], v[190:193], v[64:67]
	v_mfma_f32_16x16x32_bf16 v[76:79], v[214:217], v[190:193], v[76:79]
	v_mfma_f32_16x16x32_bf16 v[52:55], v[206:209], v[198:201], v[52:55]
	v_mfma_f32_16x16x32_bf16 v[68:71], v[214:217], v[198:201], v[68:71]
	s_setprio 0
	s_mov_b32 m0, s57
	v_lshl_add_u64 v[160:161], v[220:221], 0, s[20:21]
	s_barrier
	ds_read_b128 v[170:173], v167 offset:49152
	ds_read_b128 v[174:177], v167 offset:50176
	ds_read_b128 v[178:181], v167 offset:51200
	ds_read_b128 v[182:185], v167 offset:52224
	ds_read_b128 v[186:189], v167 offset:53248
	ds_read_b128 v[190:193], v167 offset:54272
	ds_read_b128 v[194:197], v167 offset:55296
	ds_read_b128 v[198:201], v167 offset:56320
	global_load_lds_dwordx4 v[160:161], off
	v_lshl_add_u64 v[160:161], v[224:225], 0, s[20:21]
	s_mov_b32 m0, s58
	s_nop 0
	global_load_lds_dwordx4 v[160:161], off
	s_barrier
	s_waitcnt lgkmcnt(0)
	s_setprio 1
	s_waitcnt lgkmcnt(0)
	v_mfma_f32_16x16x32_bf16 v[40:43], v[144:147], v[170:173], v[40:43]
	v_mfma_f32_16x16x32_bf16 v[32:35], v[152:155], v[170:173], v[32:35]
	v_mfma_f32_16x16x32_bf16 v[24:27], v[144:147], v[178:181], v[24:27]
	v_mfma_f32_16x16x32_bf16 v[20:23], v[152:155], v[178:181], v[20:23]
	v_mfma_f32_16x16x32_bf16 v[4:7], v[144:147], v[186:189], v[4:7]
	v_mfma_f32_16x16x32_bf16 v[124:127], v[152:155], v[186:189], v[124:127]
	v_mfma_f32_16x16x32_bf16 v[0:3], v[144:147], v[194:197], v[0:3]
	v_mfma_f32_16x16x32_bf16 v[116:119], v[152:155], v[194:197], v[116:119]
	v_mfma_f32_16x16x32_bf16 v[40:43], v[148:151], v[174:177], v[40:43]
	v_mfma_f32_16x16x32_bf16 v[32:35], v[156:159], v[174:177], v[32:35]
	v_mfma_f32_16x16x32_bf16 v[24:27], v[148:151], v[182:185], v[24:27]
	v_mfma_f32_16x16x32_bf16 v[20:23], v[156:159], v[182:185], v[20:23]
	v_mfma_f32_16x16x32_bf16 v[4:7], v[148:151], v[190:193], v[4:7]
	v_mfma_f32_16x16x32_bf16 v[124:127], v[156:159], v[190:193], v[124:127]
	v_mfma_f32_16x16x32_bf16 v[0:3], v[148:151], v[198:201], v[0:3]
	v_mfma_f32_16x16x32_bf16 v[116:119], v[156:159], v[198:201], v[116:119]
	s_setprio 0
	s_barrier
	s_add_u32 s44, s46, 0x40080
	s_addc_u32 s45, s47, 0
	s_add_i32 s46, s48, s52
	v_lshl_add_u64 v[144:145], s[44:45], 0, v[132:133]
	s_mov_b32 m0, s46
	s_nop 0
	global_load_lds_dwordx4 v[144:145], off
	v_lshl_add_u64 v[144:145], s[44:45], 0, v[128:129]
	s_add_i32 m0, s46, 0x2000
	s_nop 0
	global_load_lds_dwordx4 v[144:145], off
	s_waitcnt vmcnt(6)
	s_barrier
	s_setprio 1
	v_mfma_f32_16x16x32_bf16 v[28:31], v[202:205], v[170:173], v[28:31]
	v_mfma_f32_16x16x32_bf16 v[44:47], v[210:213], v[170:173], v[44:47]
	v_mfma_f32_16x16x32_bf16 v[16:19], v[202:205], v[178:181], v[16:19]
	v_mfma_f32_16x16x32_bf16 v[36:39], v[210:213], v[178:181], v[36:39]
	v_mfma_f32_16x16x32_bf16 v[120:123], v[202:205], v[186:189], v[120:123]
	v_mfma_f32_16x16x32_bf16 v[12:15], v[210:213], v[186:189], v[12:15]
	v_mfma_f32_16x16x32_bf16 v[112:115], v[202:205], v[194:197], v[112:115]
	v_mfma_f32_16x16x32_bf16 v[8:11], v[210:213], v[194:197], v[8:11]
	v_mfma_f32_16x16x32_bf16 v[28:31], v[206:209], v[174:177], v[28:31]
	v_mfma_f32_16x16x32_bf16 v[44:47], v[214:217], v[174:177], v[44:47]
	v_mfma_f32_16x16x32_bf16 v[16:19], v[206:209], v[182:185], v[16:19]
	v_mfma_f32_16x16x32_bf16 v[36:39], v[214:217], v[182:185], v[36:39]
	v_mfma_f32_16x16x32_bf16 v[120:123], v[206:209], v[190:193], v[120:123]
	v_mfma_f32_16x16x32_bf16 v[12:15], v[214:217], v[190:193], v[12:15]
	v_mfma_f32_16x16x32_bf16 v[112:115], v[206:209], v[198:201], v[112:115]
	v_mfma_f32_16x16x32_bf16 v[8:11], v[214:217], v[198:201], v[8:11]
	s_setprio 0
	s_add_u32 s66, s66, 0x100
	s_addc_u32 s67, s67, 0
	s_cmp_lt_i32 s68, s56
	s_mov_b64 s[44:45], s[6:7]
	s_mov_b32 s46, s68
	s_barrier
	s_cbranch_scc0 .Lpeel_done_P2b

.Lpeel_done_P2b:
.LBB0_313:
	v_cndmask_b32_e64 v144, 0, 1, s[26:27]
	v_cmp_ne_u32_e64 s[6:7], 1, v144
	s_andn2_b64 vcc, exec, s[26:27]
	s_cbranch_vccnz .LBB0_315
	s_barrier

.Lzskip_P2g:
	s_and_b64 s[6:7], s[6:7], exec
	s_cselect_b32 s45, s49, s57
	s_cselect_b32 s47, s48, s56
	s_cselect_b32 s71, s51, s55
	s_cselect_b32 s72, s50, s54
	s_add_u32 s6, s56, 0x20080
	s_addc_u32 s7, s57, 0
	s_add_u32 s73, s54, 0x100
	s_addc_u32 s74, s55, 0
	s_mov_b32 s54, 0
	v_add_u32_e32 v154, s64, v195
	ds_read_b128 v[142:145], v154
	ds_read_b128 v[146:149], v154 offset:1024
	ds_read_b128 v[150:153], v154 offset:2048
	ds_read_b128 v[154:157], v154 offset:3072
	s_add_i32 s75, s54, 2
	s_add_u32 s55, s6, 0xfffe0080
	s_addc_u32 s56, s7, -1
	s_cmp_eq_u32 s63, s54
	s_cselect_b32 s54, s72, s73
	s_cselect_b32 s57, s45, s56
	s_cselect_b32 s56, s47, s55
	s_cselect_b32 s55, s71, s74
	v_lshl_add_u64 v[190:191], s[6:7], 0, v[134:135]
	s_add_i32 m0, s19, 0xc000
	ds_read_b128 v[158:161], v201
	ds_read_b128 v[162:165], v201 offset:1024
	ds_read_b128 v[166:169], v201 offset:2048
	ds_read_b128 v[170:173], v201 offset:3072
	ds_read_b128 v[174:177], v201 offset:4096
	ds_read_b128 v[178:181], v201 offset:5120
	ds_read_b128 v[182:185], v201 offset:6144
	ds_read_b128 v[186:189], v201 offset:7168
	global_load_lds_dwordx4 v[190:191], off
	v_lshl_add_u64 v[190:191], s[6:7], 0, v[136:137]
	s_add_i32 m0, s19, 0xe000
	s_nop 0
	global_load_lds_dwordx4 v[190:191], off
	s_waitcnt lgkmcnt(8)
	s_barrier
	s_waitcnt lgkmcnt(0)
	s_setprio 1
	s_waitcnt lgkmcnt(0)
	v_mfma_i32_16x16x64_i8 v[124:127], v[142:145], v[158:161], 0
	v_mfma_i32_16x16x64_i8 v[120:123], v[150:153], v[158:161], 0
	v_mfma_i32_16x16x64_i8 v[116:119], v[142:145], v[166:169], 0
	v_mfma_i32_16x16x64_i8 v[112:115], v[150:153], v[166:169], 0
	v_mfma_i32_16x16x64_i8 v[108:111], v[142:145], v[174:177], 0
	v_mfma_i32_16x16x64_i8 v[104:107], v[150:153], v[174:177], 0
	v_mfma_i32_16x16x64_i8 v[100:103], v[142:145], v[182:185], 0
	v_mfma_i32_16x16x64_i8 v[96:99], v[150:153], v[182:185], 0
	v_mfma_i32_16x16x64_i8 v[124:127], v[146:149], v[162:165], v[124:127]
	v_mfma_i32_16x16x64_i8 v[120:123], v[154:157], v[162:165], v[120:123]
	v_mfma_i32_16x16x64_i8 v[116:119], v[146:149], v[170:173], v[116:119]
	v_mfma_i32_16x16x64_i8 v[112:115], v[154:157], v[170:173], v[112:115]
	v_mfma_i32_16x16x64_i8 v[108:111], v[146:149], v[178:181], v[108:111]
	v_mfma_i32_16x16x64_i8 v[104:107], v[154:157], v[178:181], v[104:107]
	v_mfma_i32_16x16x64_i8 v[100:103], v[146:149], v[186:189], v[100:103]
	v_mfma_i32_16x16x64_i8 v[96:99], v[154:157], v[186:189], v[96:99]
	s_setprio 0
	s_barrier
	v_add_u32_e32 v190, s65, v195
	s_add_i32 s76, s64, s18
	ds_read_b128 v[204:207], v190
	ds_read_b128 v[208:211], v190 offset:1024
	ds_read_b128 v[212:215], v190 offset:2048
	ds_read_b128 v[216:219], v190 offset:3072
	v_lshl_add_u64 v[190:191], s[54:55], 0, v[130:131]
	s_mov_b32 m0, s76
	v_lshl_add_u64 v[220:221], s[54:55], 0, v[128:129]
	global_load_lds_dwordx4 v[190:191], off
	s_add_i32 m0, s76, 0x2000
	s_nop 0
	global_load_lds_dwordx4 v[220:221], off
	s_barrier
	s_waitcnt lgkmcnt(0)
	s_setprio 1
	s_waitcnt lgkmcnt(0)
	v_mfma_i32_16x16x64_i8 v[92:95], v[204:207], v[158:161], 0
	v_mfma_i32_16x16x64_i8 v[88:91], v[212:215], v[158:161], 0
	v_mfma_i32_16x16x64_i8 v[84:87], v[204:207], v[166:169], 0
	v_mfma_i32_16x16x64_i8 v[80:83], v[212:215], v[166:169], 0
	v_mfma_i32_16x16x64_i8 v[76:79], v[204:207], v[174:177], 0
	v_mfma_i32_16x16x64_i8 v[72:75], v[212:215], v[174:177], 0
	v_mfma_i32_16x16x64_i8 v[68:71], v[204:207], v[182:185], 0
	v_mfma_i32_16x16x64_i8 v[64:67], v[212:215], v[182:185], 0
	v_mfma_i32_16x16x64_i8 v[92:95], v[208:211], v[162:165], v[92:95]
	v_mfma_i32_16x16x64_i8 v[88:91], v[216:219], v[162:165], v[88:91]
	v_mfma_i32_16x16x64_i8 v[84:87], v[208:211], v[170:173], v[84:87]
	v_mfma_i32_16x16x64_i8 v[80:83], v[216:219], v[170:173], v[80:83]
	v_mfma_i32_16x16x64_i8 v[76:79], v[208:211], v[178:181], v[76:79]
	v_mfma_i32_16x16x64_i8 v[72:75], v[216:219], v[178:181], v[72:75]
	v_mfma_i32_16x16x64_i8 v[68:71], v[208:211], v[186:189], v[68:71]
	v_mfma_i32_16x16x64_i8 v[64:67], v[216:219], v[186:189], v[64:67]
	s_setprio 0
	s_mov_b32 m0, s19
	v_lshl_add_u64 v[224:225], s[56:57], 0, v[130:131]
	s_barrier
	ds_read_b128 v[158:161], v201 offset:16384
	ds_read_b128 v[162:165], v201 offset:17408
	ds_read_b128 v[166:169], v201 offset:18432
	ds_read_b128 v[170:173], v201 offset:19456
	ds_read_b128 v[174:177], v201 offset:20480
	ds_read_b128 v[178:181], v201 offset:21504
	ds_read_b128 v[182:185], v201 offset:22528
	ds_read_b128 v[186:189], v201 offset:23552
	global_load_lds_dwordx4 v[224:225], off
	v_lshl_add_u64 v[228:229], s[56:57], 0, v[128:129]
	s_mov_b32 m0, s53
	s_nop 0
	global_load_lds_dwordx4 v[228:229], off
	s_barrier
	s_waitcnt lgkmcnt(0)
	s_setprio 1
	s_waitcnt lgkmcnt(0)
	v_mfma_i32_16x16x64_i8 v[60:63], v[142:145], v[158:161], 0
	v_mfma_i32_16x16x64_i8 v[56:59], v[150:153], v[158:161], 0
	v_mfma_i32_16x16x64_i8 v[52:55], v[142:145], v[166:169], 0
	v_mfma_i32_16x16x64_i8 v[48:51], v[150:153], v[166:169], 0
	v_mfma_i32_16x16x64_i8 v[44:47], v[142:145], v[174:177], 0
	v_mfma_i32_16x16x64_i8 v[40:43], v[150:153], v[174:177], 0
	v_mfma_i32_16x16x64_i8 v[36:39], v[142:145], v[182:185], 0
	v_mfma_i32_16x16x64_i8 v[32:35], v[150:153], v[182:185], 0
	v_mfma_i32_16x16x64_i8 v[60:63], v[146:149], v[162:165], v[60:63]
	v_mfma_i32_16x16x64_i8 v[56:59], v[154:157], v[162:165], v[56:59]
	v_mfma_i32_16x16x64_i8 v[52:55], v[146:149], v[170:173], v[52:55]
	v_mfma_i32_16x16x64_i8 v[48:51], v[154:157], v[170:173], v[48:51]
	v_mfma_i32_16x16x64_i8 v[44:47], v[146:149], v[178:181], v[44:47]
	v_mfma_i32_16x16x64_i8 v[40:43], v[154:157], v[178:181], v[40:43]
	v_mfma_i32_16x16x64_i8 v[36:39], v[146:149], v[186:189], v[36:39]
	v_mfma_i32_16x16x64_i8 v[32:35], v[154:157], v[186:189], v[32:35]
	s_setprio 0
	s_barrier
	s_add_u32 s76, s54, 0x20000
	s_addc_u32 s77, s55, 0
	s_add_i32 s78, s65, s18
	v_lshl_add_u64 v[142:143], s[76:77], 0, v[130:131]
	s_mov_b32 m0, s78
	s_nop 0
	global_load_lds_dwordx4 v[142:143], off
	v_lshl_add_u64 v[142:143], s[76:77], 0, v[128:129]
	s_add_i32 m0, s78, 0x2000
	s_nop 0
	global_load_lds_dwordx4 v[142:143], off
	s_waitcnt vmcnt(6)
	s_barrier
	s_setprio 1
	v_mfma_i32_16x16x64_i8 v[28:31], v[204:207], v[158:161], 0
	v_mfma_i32_16x16x64_i8 v[24:27], v[212:215], v[158:161], 0
	v_mfma_i32_16x16x64_i8 v[20:23], v[204:207], v[166:169], 0
	v_mfma_i32_16x16x64_i8 v[16:19], v[212:215], v[166:169], 0
	v_mfma_i32_16x16x64_i8 v[12:15], v[204:207], v[174:177], 0
	v_mfma_i32_16x16x64_i8 v[8:11], v[212:215], v[174:177], 0
	v_mfma_i32_16x16x64_i8 v[4:7], v[204:207], v[182:185], 0
	v_mfma_i32_16x16x64_i8 v[0:3], v[212:215], v[182:185], 0
	v_mfma_i32_16x16x64_i8 v[28:31], v[208:211], v[162:165], v[28:31]
	v_mfma_i32_16x16x64_i8 v[24:27], v[216:219], v[162:165], v[24:27]
	v_mfma_i32_16x16x64_i8 v[20:23], v[208:211], v[170:173], v[20:23]
	v_mfma_i32_16x16x64_i8 v[16:19], v[216:219], v[170:173], v[16:19]
	v_mfma_i32_16x16x64_i8 v[12:15], v[208:211], v[178:181], v[12:15]
	v_mfma_i32_16x16x64_i8 v[8:11], v[216:219], v[178:181], v[8:11]
	v_mfma_i32_16x16x64_i8 v[4:7], v[208:211], v[186:189], v[4:7]
	v_mfma_i32_16x16x64_i8 v[0:3], v[216:219], v[186:189], v[0:3]
	s_setprio 0
	s_add_i32 s76, 0, 0x18000
	v_add_u32_e32 v154, s76, v195
	s_barrier
	ds_read_b128 v[142:145], v154
	ds_read_b128 v[146:149], v154 offset:1024
	ds_read_b128 v[150:153], v154 offset:2048
	ds_read_b128 v[154:157], v154 offset:3072
	s_add_u32 s56, s56, 0x20000
	s_addc_u32 s57, s57, 0
	s_mov_b32 m0, s58
	v_lshl_add_u64 v[204:205], s[56:57], 0, v[130:131]
	ds_read_b128 v[158:161], v201 offset:32768
	ds_read_b128 v[162:165], v201 offset:33792
	ds_read_b128 v[166:169], v201 offset:34816
	ds_read_b128 v[170:173], v201 offset:35840
	ds_read_b128 v[174:177], v201 offset:36864
	ds_read_b128 v[178:181], v201 offset:37888
	ds_read_b128 v[182:185], v201 offset:38912
	ds_read_b128 v[186:189], v201 offset:39936
	global_load_lds_dwordx4 v[204:205], off
	v_lshl_add_u64 v[204:205], s[56:57], 0, v[128:129]
	s_mov_b32 m0, s59
	s_nop 0
	global_load_lds_dwordx4 v[204:205], off
	s_waitcnt lgkmcnt(8)
	s_barrier
	s_waitcnt lgkmcnt(0)
	s_setprio 1
	s_waitcnt lgkmcnt(0)
	v_mfma_i32_16x16x64_i8 v[124:127], v[142:145], v[158:161], v[124:127]
	v_mfma_i32_16x16x64_i8 v[120:123], v[150:153], v[158:161], v[120:123]
	v_mfma_i32_16x16x64_i8 v[116:119], v[142:145], v[166:169], v[116:119]
	v_mfma_i32_16x16x64_i8 v[112:115], v[150:153], v[166:169], v[112:115]
	v_mfma_i32_16x16x64_i8 v[108:111], v[142:145], v[174:177], v[108:111]
	v_mfma_i32_16x16x64_i8 v[104:107], v[150:153], v[174:177], v[104:107]
	v_mfma_i32_16x16x64_i8 v[100:103], v[142:145], v[182:185], v[100:103]
	v_mfma_i32_16x16x64_i8 v[96:99], v[150:153], v[182:185], v[96:99]
	v_mfma_i32_16x16x64_i8 v[124:127], v[146:149], v[162:165], v[124:127]
	v_mfma_i32_16x16x64_i8 v[120:123], v[154:157], v[162:165], v[120:123]
	v_mfma_i32_16x16x64_i8 v[116:119], v[146:149], v[170:173], v[116:119]
	v_mfma_i32_16x16x64_i8 v[112:115], v[154:157], v[170:173], v[112:115]
	v_mfma_i32_16x16x64_i8 v[108:111], v[146:149], v[178:181], v[108:111]
	v_mfma_i32_16x16x64_i8 v[104:107], v[154:157], v[178:181], v[104:107]
	v_mfma_i32_16x16x64_i8 v[100:103], v[146:149], v[186:189], v[100:103]
	v_mfma_i32_16x16x64_i8 v[96:99], v[154:157], v[186:189], v[96:99]
	s_setprio 0
	s_barrier
	s_add_i32 s56, 0, 0x1c000
	s_add_i32 s57, s76, s18
	v_add_u32_e32 v192, s56, v195
	v_lshl_add_u64 v[190:191], v[190:191], 0, s[30:31]
	s_mov_b32 m0, s57
	ds_read_b128 v[204:207], v192
	ds_read_b128 v[208:211], v192 offset:1024
	ds_read_b128 v[212:215], v192 offset:2048
	ds_read_b128 v[216:219], v192 offset:3072
	global_load_lds_dwordx4 v[190:191], off
	v_lshl_add_u64 v[190:191], v[220:221], 0, s[30:31]
	s_add_i32 m0, s57, 0x2000
	s_nop 0
	global_load_lds_dwordx4 v[190:191], off
	s_barrier
	s_waitcnt lgkmcnt(0)
	s_setprio 1
	s_waitcnt lgkmcnt(0)
	v_mfma_i32_16x16x64_i8 v[92:95], v[204:207], v[158:161], v[92:95]
	v_mfma_i32_16x16x64_i8 v[88:91], v[212:215], v[158:161], v[88:91]
	v_mfma_i32_16x16x64_i8 v[84:87], v[204:207], v[166:169], v[84:87]
	v_mfma_i32_16x16x64_i8 v[80:83], v[212:215], v[166:169], v[80:83]
	v_mfma_i32_16x16x64_i8 v[76:79], v[204:207], v[174:177], v[76:79]
	v_mfma_i32_16x16x64_i8 v[72:75], v[212:215], v[174:177], v[72:75]
	v_mfma_i32_16x16x64_i8 v[68:71], v[204:207], v[182:185], v[68:71]
	v_mfma_i32_16x16x64_i8 v[64:67], v[212:215], v[182:185], v[64:67]
	v_mfma_i32_16x16x64_i8 v[92:95], v[208:211], v[162:165], v[92:95]
	v_mfma_i32_16x16x64_i8 v[88:91], v[216:219], v[162:165], v[88:91]
	v_mfma_i32_16x16x64_i8 v[84:87], v[208:211], v[170:173], v[84:87]
	v_mfma_i32_16x16x64_i8 v[80:83], v[216:219], v[170:173], v[80:83]
	v_mfma_i32_16x16x64_i8 v[76:79], v[208:211], v[178:181], v[76:79]
	v_mfma_i32_16x16x64_i8 v[72:75], v[216:219], v[178:181], v[72:75]
	v_mfma_i32_16x16x64_i8 v[68:71], v[208:211], v[186:189], v[68:71]
	v_mfma_i32_16x16x64_i8 v[64:67], v[216:219], v[186:189], v[64:67]
	s_setprio 0
	s_mov_b32 m0, s61
	v_lshl_add_u64 v[190:191], v[224:225], 0, s[30:31]
	s_barrier
	ds_read_b128 v[158:161], v201 offset:49152
	ds_read_b128 v[162:165], v201 offset:50176
	ds_read_b128 v[166:169], v201 offset:51200
	ds_read_b128 v[170:173], v201 offset:52224
	ds_read_b128 v[174:177], v201 offset:53248
	ds_read_b128 v[178:181], v201 offset:54272
	ds_read_b128 v[182:185], v201 offset:55296
	ds_read_b128 v[186:189], v201 offset:56320
	global_load_lds_dwordx4 v[190:191], off
	v_lshl_add_u64 v[190:191], v[228:229], 0, s[30:31]
	s_mov_b32 m0, s62
	s_nop 0
	global_load_lds_dwordx4 v[190:191], off
	s_barrier
	s_waitcnt lgkmcnt(0)
	s_setprio 1
	s_waitcnt lgkmcnt(0)
	v_mfma_i32_16x16x64_i8 v[60:63], v[142:145], v[158:161], v[60:63]
	v_mfma_i32_16x16x64_i8 v[56:59], v[150:153], v[158:161], v[56:59]
	v_mfma_i32_16x16x64_i8 v[52:55], v[142:145], v[166:169], v[52:55]
	v_mfma_i32_16x16x64_i8 v[48:51], v[150:153], v[166:169], v[48:51]
	v_mfma_i32_16x16x64_i8 v[44:47], v[142:145], v[174:177], v[44:47]
	v_mfma_i32_16x16x64_i8 v[40:43], v[150:153], v[174:177], v[40:43]
	v_mfma_i32_16x16x64_i8 v[36:39], v[142:145], v[182:185], v[36:39]
	v_mfma_i32_16x16x64_i8 v[32:35], v[150:153], v[182:185], v[32:35]
	v_mfma_i32_16x16x64_i8 v[60:63], v[146:149], v[162:165], v[60:63]
	v_mfma_i32_16x16x64_i8 v[56:59], v[154:157], v[162:165], v[56:59]
	v_mfma_i32_16x16x64_i8 v[52:55], v[146:149], v[170:173], v[52:55]
	v_mfma_i32_16x16x64_i8 v[48:51], v[154:157], v[170:173], v[48:51]
	v_mfma_i32_16x16x64_i8 v[44:47], v[146:149], v[178:181], v[44:47]
	v_mfma_i32_16x16x64_i8 v[40:43], v[154:157], v[178:181], v[40:43]
	v_mfma_i32_16x16x64_i8 v[36:39], v[146:149], v[186:189], v[36:39]
	v_mfma_i32_16x16x64_i8 v[32:35], v[154:157], v[186:189], v[32:35]
	s_setprio 0
	s_barrier
	s_add_u32 s54, s54, 0x20080
	s_addc_u32 s55, s55, 0
	s_add_i32 s56, s56, s18
	v_lshl_add_u64 v[142:143], s[54:55], 0, v[130:131]
	s_mov_b32 m0, s56
	s_nop 0
	global_load_lds_dwordx4 v[142:143], off
	v_lshl_add_u64 v[142:143], s[54:55], 0, v[128:129]
	s_add_i32 m0, s56, 0x2000
	s_nop 0
	global_load_lds_dwordx4 v[142:143], off
	s_waitcnt vmcnt(6)
	s_barrier
	s_setprio 1
	v_mfma_i32_16x16x64_i8 v[28:31], v[204:207], v[158:161], v[28:31]
	v_mfma_i32_16x16x64_i8 v[24:27], v[212:215], v[158:161], v[24:27]
	v_mfma_i32_16x16x64_i8 v[20:23], v[204:207], v[166:169], v[20:23]
	v_mfma_i32_16x16x64_i8 v[16:19], v[212:215], v[166:169], v[16:19]
	v_mfma_i32_16x16x64_i8 v[12:15], v[204:207], v[174:177], v[12:15]
	v_mfma_i32_16x16x64_i8 v[8:11], v[212:215], v[174:177], v[8:11]
	v_mfma_i32_16x16x64_i8 v[4:7], v[204:207], v[182:185], v[4:7]
	v_mfma_i32_16x16x64_i8 v[0:3], v[212:215], v[182:185], v[0:3]
	v_mfma_i32_16x16x64_i8 v[28:31], v[208:211], v[162:165], v[28:31]
	v_mfma_i32_16x16x64_i8 v[24:27], v[216:219], v[162:165], v[24:27]
	v_mfma_i32_16x16x64_i8 v[20:23], v[208:211], v[170:173], v[20:23]
	v_mfma_i32_16x16x64_i8 v[16:19], v[216:219], v[170:173], v[16:19]
	v_mfma_i32_16x16x64_i8 v[12:15], v[208:211], v[178:181], v[12:15]
	v_mfma_i32_16x16x64_i8 v[8:11], v[216:219], v[178:181], v[8:11]
	v_mfma_i32_16x16x64_i8 v[4:7], v[208:211], v[186:189], v[4:7]
	v_mfma_i32_16x16x64_i8 v[0:3], v[216:219], v[186:189], v[0:3]
	s_setprio 0
	s_add_u32 s6, s6, 0x100
	s_addc_u32 s7, s7, 0
	s_add_u32 s73, s73, 0x100
	s_addc_u32 s74, s74, 0
	s_cmp_ge_i32 s75, s60
	s_mov_b32 s54, s75
	s_barrier
	s_cbranch_scc1 .Lpeel_done_P2g

.Lpeel_done_P2g:
	v_cvt_f32_i32_e32 v188, v124
	v_cvt_f32_i32_e32 v189, v125
	v_cvt_f32_i32_e32 v190, v126
	v_cvt_f32_i32_e32 v191, v127
	v_cvt_f32_i32_e32 v124, v120
	v_cvt_f32_i32_e32 v125, v121
	v_cvt_f32_i32_e32 v186, v122
	v_cvt_f32_i32_e32 v187, v123
	v_cvt_f32_i32_e32 v120, v116
	v_cvt_f32_i32_e32 v121, v117
	v_cvt_f32_i32_e32 v184, v118
	v_cvt_f32_i32_e32 v185, v119
	v_cvt_f32_i32_e32 v116, v112
	v_cvt_f32_i32_e32 v117, v113
	v_cvt_f32_i32_e32 v144, v114
	v_cvt_f32_i32_e32 v145, v115
	v_cvt_f32_i32_e32 v114, v108
	v_cvt_f32_i32_e32 v115, v109
	v_cvt_f32_i32_e32 v142, v110
	v_cvt_f32_i32_e32 v143, v111
	v_cvt_f32_i32_e32 v112, v104
	v_cvt_f32_i32_e32 v113, v105
	v_cvt_f32_i32_e32 v126, v106
	v_cvt_f32_i32_e32 v127, v107
	v_cvt_f32_i32_e32 v110, v100
	v_cvt_f32_i32_e32 v111, v101
	v_cvt_f32_i32_e32 v122, v102
	v_cvt_f32_i32_e32 v123, v103
	v_cvt_f32_i32_e32 v106, v96
	v_cvt_f32_i32_e32 v107, v97
	v_cvt_f32_i32_e32 v118, v98
	v_cvt_f32_i32_e32 v119, v99
	v_cvt_f32_i32_e32 v96, v92
	v_cvt_f32_i32_e32 v97, v93
	v_cvt_f32_i32_e32 v108, v94
	v_cvt_f32_i32_e32 v109, v95
	v_cvt_f32_i32_e32 v92, v88
	v_cvt_f32_i32_e32 v93, v89
	v_cvt_f32_i32_e32 v104, v90
	v_cvt_f32_i32_e32 v105, v91
	v_cvt_f32_i32_e32 v90, v84
	v_cvt_f32_i32_e32 v91, v85
	v_cvt_f32_i32_e32 v102, v86
	v_cvt_f32_i32_e32 v103, v87
	v_cvt_f32_i32_e32 v84, v80
	v_cvt_f32_i32_e32 v85, v81
	v_cvt_f32_i32_e32 v100, v82
	v_cvt_f32_i32_e32 v101, v83
	v_cvt_f32_i32_e32 v82, v76
	v_cvt_f32_i32_e32 v83, v77
	v_cvt_f32_i32_e32 v98, v78
	v_cvt_f32_i32_e32 v99, v79
	v_cvt_f32_i32_e32 v80, v72
	v_cvt_f32_i32_e32 v81, v73
	v_cvt_f32_i32_e32 v86, v74
	v_cvt_f32_i32_e32 v87, v75
	v_cvt_f32_i32_e32 v76, v68
	v_cvt_f32_i32_e32 v77, v69
	v_cvt_f32_i32_e32 v70, v70
	v_cvt_f32_i32_e32 v71, v71
	v_cvt_f32_i32_e32 v64, v64
	v_cvt_f32_i32_e32 v65, v65
	v_cvt_f32_i32_e32 v66, v66
	v_cvt_f32_i32_e32 v67, v67
	v_cvt_f32_i32_e32 v174, v60
	v_cvt_f32_i32_e32 v175, v61
	v_cvt_f32_i32_e32 v60, v62
	v_cvt_f32_i32_e32 v61, v63
	v_cvt_f32_i32_e32 v168, v56
	v_cvt_f32_i32_e32 v169, v57
	v_cvt_f32_i32_e32 v182, v58
	v_cvt_f32_i32_e32 v183, v59
	v_cvt_f32_i32_e32 v166, v52
	v_cvt_f32_i32_e32 v167, v53
	v_cvt_f32_i32_e32 v180, v54
	v_cvt_f32_i32_e32 v181, v55
	v_cvt_f32_i32_e32 v88, v48
	v_cvt_f32_i32_e32 v89, v49
	v_cvt_f32_i32_e32 v178, v50
	v_cvt_f32_i32_e32 v179, v51
	v_cvt_f32_i32_e32 v78, v44
	v_cvt_f32_i32_e32 v79, v45
	v_cvt_f32_i32_e32 v176, v46
	v_cvt_f32_i32_e32 v177, v47
	v_cvt_f32_i32_e32 v74, v40
	v_cvt_f32_i32_e32 v75, v41
	v_cvt_f32_i32_e32 v172, v42
	v_cvt_f32_i32_e32 v173, v43
	v_cvt_f32_i32_e32 v72, v36
	v_cvt_f32_i32_e32 v73, v37
	v_cvt_f32_i32_e32 v170, v38
	v_cvt_f32_i32_e32 v171, v39
	v_cvt_f32_i32_e32 v68, v32
	v_cvt_f32_i32_e32 v69, v33
	v_cvt_f32_i32_e32 v164, v34
	v_cvt_f32_i32_e32 v165, v35
	v_cvt_f32_i32_e32 v62, v28
	v_cvt_f32_i32_e32 v63, v29
	v_cvt_f32_i32_e32 v162, v30
	v_cvt_f32_i32_e32 v163, v31
	v_cvt_f32_i32_e32 v58, v24
	v_cvt_f32_i32_e32 v59, v25
	v_cvt_f32_i32_e32 v94, v26
	v_cvt_f32_i32_e32 v95, v27
	v_cvt_f32_i32_e32 v56, v20
	v_cvt_f32_i32_e32 v57, v21
	v_cvt_f32_i32_e32 v160, v22
	v_cvt_f32_i32_e32 v161, v23
	v_cvt_f32_i32_e32 v40, v16
	v_cvt_f32_i32_e32 v41, v17
	v_cvt_f32_i32_e32 v158, v18
	v_cvt_f32_i32_e32 v159, v19
	v_cvt_f32_i32_e32 v36, v12
	v_cvt_f32_i32_e32 v37, v13
	v_cvt_f32_i32_e32 v156, v14
	v_cvt_f32_i32_e32 v157, v15
	v_cvt_f32_i32_e32 v48, v8
	v_cvt_f32_i32_e32 v49, v9
	v_cvt_f32_i32_e32 v154, v10
	v_cvt_f32_i32_e32 v155, v11
	v_cvt_f32_i32_e32 v148, v4
	v_cvt_f32_i32_e32 v149, v5
	v_cvt_f32_i32_e32 v152, v6
	v_cvt_f32_i32_e32 v153, v7
	v_cvt_f32_i32_e32 v146, v0
	v_cvt_f32_i32_e32 v147, v1
	v_cvt_f32_i32_e32 v150, v2
	v_cvt_f32_i32_e32 v151, v3

.Lzskip_P2r:
	s_and_b64 s[8:9], s[8:9], exec
	s_cselect_b32 s47, s51, s57
	s_cselect_b32 s49, s50, s56
	s_cselect_b32 s73, s53, s59
	s_cselect_b32 s74, s52, s58
	s_add_u32 s75, s58, 0x100
	s_addc_u32 s76, s59, 0
	s_mov_b32 s58, 0
	v_add_u32_e32 v156, s71, v224
	ds_read_b128 v[144:147], v156
	ds_read_b128 v[148:151], v156 offset:1024
	ds_read_b128 v[152:155], v156 offset:2048
	ds_read_b128 v[156:159], v156 offset:3072
	s_add_i32 s77, s58, 2
	s_add_u32 s8, s56, 0x100
	s_addc_u32 s9, s57, 0
	s_cmp_eq_u32 s70, s58
	s_cselect_b32 s58, s74, s75
	s_cselect_b32 s61, s47, s9
	s_cselect_b32 s60, s49, s8
	s_cselect_b32 s59, s73, s76
	v_lshl_add_u64 v[192:193], s[56:57], 0, v[136:137]
	s_add_i32 m0, s62, 0xc000
	ds_read_b128 v[160:163], v232
	ds_read_b128 v[164:167], v232 offset:1024
	ds_read_b128 v[168:171], v232 offset:2048
	ds_read_b128 v[172:175], v232 offset:3072
	ds_read_b128 v[176:179], v232 offset:4096
	ds_read_b128 v[180:183], v232 offset:5120
	ds_read_b128 v[184:187], v232 offset:6144
	ds_read_b128 v[188:191], v232 offset:7168
	global_load_lds_dwordx4 v[192:193], off
	v_lshl_add_u64 v[192:193], s[56:57], 0, v[138:139]
	s_add_i32 m0, s62, 0xe000
	s_nop 0
	global_load_lds_dwordx4 v[192:193], off
	s_waitcnt lgkmcnt(8)
	s_barrier
	s_waitcnt lgkmcnt(0)
	s_setprio 1
	s_waitcnt lgkmcnt(0)
	v_mfma_i32_16x16x64_i8 v[124:127], v[144:147], v[160:163], 0
	v_mfma_i32_16x16x64_i8 v[112:115], v[152:155], v[160:163], 0
	v_mfma_i32_16x16x64_i8 v[120:123], v[144:147], v[168:171], 0
	v_mfma_i32_16x16x64_i8 v[104:107], v[152:155], v[168:171], 0
	v_mfma_i32_16x16x64_i8 v[116:119], v[144:147], v[176:179], 0
	v_mfma_i32_16x16x64_i8 v[100:103], v[152:155], v[176:179], 0
	v_mfma_i32_16x16x64_i8 v[108:111], v[144:147], v[184:187], 0
	v_mfma_i32_16x16x64_i8 v[96:99], v[152:155], v[184:187], 0
	v_mfma_i32_16x16x64_i8 v[124:127], v[148:151], v[164:167], v[124:127]
	v_mfma_i32_16x16x64_i8 v[112:115], v[156:159], v[164:167], v[112:115]
	v_mfma_i32_16x16x64_i8 v[120:123], v[148:151], v[172:175], v[120:123]
	v_mfma_i32_16x16x64_i8 v[104:107], v[156:159], v[172:175], v[104:107]
	v_mfma_i32_16x16x64_i8 v[116:119], v[148:151], v[180:183], v[116:119]
	v_mfma_i32_16x16x64_i8 v[100:103], v[156:159], v[180:183], v[100:103]
	v_mfma_i32_16x16x64_i8 v[108:111], v[148:151], v[188:191], v[108:111]
	v_mfma_i32_16x16x64_i8 v[96:99], v[156:159], v[188:191], v[96:99]
	s_setprio 0
	s_barrier
	s_add_i32 s20, s71, s19
	v_add_u32_e32 v204, s72, v224
	v_lshl_add_u64 v[208:209], s[58:59], 0, v[132:133]
	s_mov_b32 m0, s20
	ds_read_b128 v[192:195], v204
	ds_read_b128 v[196:199], v204 offset:1024
	ds_read_b128 v[200:203], v204 offset:2048
	ds_read_b128 v[204:207], v204 offset:3072
	global_load_lds_dwordx4 v[208:209], off
	v_lshl_add_u64 v[210:211], s[58:59], 0, v[128:129]
	s_add_i32 m0, s20, 0x2000
	s_nop 0
	global_load_lds_dwordx4 v[210:211], off
	s_barrier
	s_waitcnt lgkmcnt(0)
	s_setprio 1
	s_waitcnt lgkmcnt(0)
	v_mfma_i32_16x16x64_i8 v[84:87], v[192:195], v[160:163], 0
	v_mfma_i32_16x16x64_i8 v[56:59], v[200:203], v[160:163], 0
	v_mfma_i32_16x16x64_i8 v[76:79], v[192:195], v[168:171], 0
	v_mfma_i32_16x16x64_i8 v[44:47], v[200:203], v[168:171], 0
	v_mfma_i32_16x16x64_i8 v[64:67], v[192:195], v[176:179], 0
	v_mfma_i32_16x16x64_i8 v[36:39], v[200:203], v[176:179], 0
	v_mfma_i32_16x16x64_i8 v[52:55], v[192:195], v[184:187], 0
	v_mfma_i32_16x16x64_i8 v[28:31], v[200:203], v[184:187], 0
	v_mfma_i32_16x16x64_i8 v[84:87], v[196:199], v[164:167], v[84:87]
	v_mfma_i32_16x16x64_i8 v[56:59], v[204:207], v[164:167], v[56:59]
	v_mfma_i32_16x16x64_i8 v[76:79], v[196:199], v[172:175], v[76:79]
	v_mfma_i32_16x16x64_i8 v[44:47], v[204:207], v[172:175], v[44:47]
	v_mfma_i32_16x16x64_i8 v[64:67], v[196:199], v[180:183], v[64:67]
	v_mfma_i32_16x16x64_i8 v[36:39], v[204:207], v[180:183], v[36:39]
	v_mfma_i32_16x16x64_i8 v[52:55], v[196:199], v[188:191], v[52:55]
	v_mfma_i32_16x16x64_i8 v[28:31], v[204:207], v[188:191], v[28:31]
	s_setprio 0
	s_mov_b32 m0, s62
	v_lshl_add_u64 v[212:213], s[60:61], 0, v[134:135]
	s_barrier
	ds_read_b128 v[160:163], v232 offset:16384
	ds_read_b128 v[164:167], v232 offset:17408
	ds_read_b128 v[168:171], v232 offset:18432
	ds_read_b128 v[172:175], v232 offset:19456
	ds_read_b128 v[176:179], v232 offset:20480
	ds_read_b128 v[180:183], v232 offset:21504
	ds_read_b128 v[184:187], v232 offset:22528
	ds_read_b128 v[188:191], v232 offset:23552
	global_load_lds_dwordx4 v[212:213], off
	v_lshl_add_u64 v[214:215], s[60:61], 0, v[130:131]
	s_mov_b32 m0, s63
	s_nop 0
	global_load_lds_dwordx4 v[214:215], off
	s_barrier
	s_waitcnt lgkmcnt(0)
	s_setprio 1
	s_waitcnt lgkmcnt(0)
	v_mfma_i32_16x16x64_i8 v[92:95], v[144:147], v[160:163], 0
	v_mfma_i32_16x16x64_i8 v[72:75], v[152:155], v[160:163], 0
	v_mfma_i32_16x16x64_i8 v[88:91], v[144:147], v[168:171], 0
	v_mfma_i32_16x16x64_i8 v[60:63], v[152:155], v[168:171], 0
	v_mfma_i32_16x16x64_i8 v[80:83], v[144:147], v[176:179], 0
	v_mfma_i32_16x16x64_i8 v[48:51], v[152:155], v[176:179], 0
	v_mfma_i32_16x16x64_i8 v[68:71], v[144:147], v[184:187], 0
	v_mfma_i32_16x16x64_i8 v[40:43], v[152:155], v[184:187], 0
	v_mfma_i32_16x16x64_i8 v[92:95], v[148:151], v[164:167], v[92:95]
	v_mfma_i32_16x16x64_i8 v[72:75], v[156:159], v[164:167], v[72:75]
	v_mfma_i32_16x16x64_i8 v[88:91], v[148:151], v[172:175], v[88:91]
	v_mfma_i32_16x16x64_i8 v[60:63], v[156:159], v[172:175], v[60:63]
	v_mfma_i32_16x16x64_i8 v[80:83], v[148:151], v[180:183], v[80:83]
	v_mfma_i32_16x16x64_i8 v[48:51], v[156:159], v[180:183], v[48:51]
	v_mfma_i32_16x16x64_i8 v[68:71], v[148:151], v[188:191], v[68:71]
	v_mfma_i32_16x16x64_i8 v[40:43], v[156:159], v[188:191], v[40:43]
	s_setprio 0
	s_barrier
	s_add_u32 s20, s58, 0x20000
	s_addc_u32 s21, s59, 0
	s_add_i32 s56, s72, s19
	v_lshl_add_u64 v[144:145], s[20:21], 0, v[132:133]
	s_mov_b32 m0, s56
	s_nop 0
	global_load_lds_dwordx4 v[144:145], off
	v_lshl_add_u64 v[144:145], s[20:21], 0, v[128:129]
	s_add_i32 m0, s56, 0x2000
	s_nop 0
	global_load_lds_dwordx4 v[144:145], off
	s_waitcnt vmcnt(6)
	s_barrier
	s_setprio 1
	v_mfma_i32_16x16x64_i8 v[32:35], v[192:195], v[160:163], 0
	v_mfma_i32_16x16x64_i8 v[8:11], v[200:203], v[160:163], 0
	v_mfma_i32_16x16x64_i8 v[24:27], v[192:195], v[168:171], 0
	v_mfma_i32_16x16x64_i8 v[12:15], v[200:203], v[168:171], 0
	v_mfma_i32_16x16x64_i8 v[20:23], v[192:195], v[176:179], 0
	v_mfma_i32_16x16x64_i8 v[4:7], v[200:203], v[176:179], 0
	v_mfma_i32_16x16x64_i8 v[16:19], v[192:195], v[184:187], 0
	v_mfma_i32_16x16x64_i8 v[0:3], v[200:203], v[184:187], 0
	v_mfma_i32_16x16x64_i8 v[32:35], v[196:199], v[164:167], v[32:35]
	v_mfma_i32_16x16x64_i8 v[8:11], v[204:207], v[164:167], v[8:11]
	v_mfma_i32_16x16x64_i8 v[24:27], v[196:199], v[172:175], v[24:27]
	v_mfma_i32_16x16x64_i8 v[12:15], v[204:207], v[172:175], v[12:15]
	v_mfma_i32_16x16x64_i8 v[20:23], v[196:199], v[180:183], v[20:23]
	v_mfma_i32_16x16x64_i8 v[4:7], v[204:207], v[180:183], v[4:7]
	v_mfma_i32_16x16x64_i8 v[16:19], v[196:199], v[188:191], v[16:19]
	v_mfma_i32_16x16x64_i8 v[0:3], v[204:207], v[188:191], v[0:3]
	s_setprio 0
	s_add_i32 s56, 0, 0x18000
	v_add_u32_e32 v156, s56, v224
	s_barrier
	ds_read_b128 v[144:147], v156
	ds_read_b128 v[148:151], v156 offset:1024
	ds_read_b128 v[152:155], v156 offset:2048
	ds_read_b128 v[156:159], v156 offset:3072
	s_add_u32 s20, s60, 0x1000
	s_addc_u32 s21, s61, 0
	s_mov_b32 m0, s64
	v_lshl_add_u64 v[192:193], s[20:21], 0, v[134:135]
	ds_read_b128 v[160:163], v232 offset:32768
	ds_read_b128 v[164:167], v232 offset:33792
	ds_read_b128 v[168:171], v232 offset:34816
	ds_read_b128 v[172:175], v232 offset:35840
	ds_read_b128 v[176:179], v232 offset:36864
	ds_read_b128 v[180:183], v232 offset:37888
	ds_read_b128 v[184:187], v232 offset:38912
	ds_read_b128 v[188:191], v232 offset:39936
	global_load_lds_dwordx4 v[192:193], off
	v_lshl_add_u64 v[192:193], s[20:21], 0, v[130:131]
	s_mov_b32 m0, s65
	s_nop 0
	global_load_lds_dwordx4 v[192:193], off
	s_waitcnt lgkmcnt(8)
	s_barrier
	s_waitcnt lgkmcnt(0)
	s_setprio 1
	s_waitcnt lgkmcnt(0)
	v_mfma_i32_16x16x64_i8 v[124:127], v[144:147], v[160:163], v[124:127]
	v_mfma_i32_16x16x64_i8 v[112:115], v[152:155], v[160:163], v[112:115]
	v_mfma_i32_16x16x64_i8 v[120:123], v[144:147], v[168:171], v[120:123]
	v_mfma_i32_16x16x64_i8 v[104:107], v[152:155], v[168:171], v[104:107]
	v_mfma_i32_16x16x64_i8 v[116:119], v[144:147], v[176:179], v[116:119]
	v_mfma_i32_16x16x64_i8 v[100:103], v[152:155], v[176:179], v[100:103]
	v_mfma_i32_16x16x64_i8 v[108:111], v[144:147], v[184:187], v[108:111]
	v_mfma_i32_16x16x64_i8 v[96:99], v[152:155], v[184:187], v[96:99]
	v_mfma_i32_16x16x64_i8 v[124:127], v[148:151], v[164:167], v[124:127]
	v_mfma_i32_16x16x64_i8 v[112:115], v[156:159], v[164:167], v[112:115]
	v_mfma_i32_16x16x64_i8 v[120:123], v[148:151], v[172:175], v[120:123]
	v_mfma_i32_16x16x64_i8 v[104:107], v[156:159], v[172:175], v[104:107]
	v_mfma_i32_16x16x64_i8 v[116:119], v[148:151], v[180:183], v[116:119]
	v_mfma_i32_16x16x64_i8 v[100:103], v[156:159], v[180:183], v[100:103]
	v_mfma_i32_16x16x64_i8 v[108:111], v[148:151], v[188:191], v[108:111]
	v_mfma_i32_16x16x64_i8 v[96:99], v[156:159], v[188:191], v[96:99]
	s_setprio 0
	s_barrier
	s_add_i32 s57, 0, 0x1c000
	s_add_i32 s20, s56, s19
	v_add_u32_e32 v204, s57, v224
	v_lshl_add_u64 v[208:209], v[208:209], 0, s[34:35]
	s_mov_b32 m0, s20
	ds_read_b128 v[192:195], v204
	ds_read_b128 v[196:199], v204 offset:1024
	ds_read_b128 v[200:203], v204 offset:2048
	ds_read_b128 v[204:207], v204 offset:3072
	global_load_lds_dwordx4 v[208:209], off
	v_lshl_add_u64 v[208:209], v[210:211], 0, s[34:35]
	s_add_i32 m0, s20, 0x2000
	s_nop 0
	global_load_lds_dwordx4 v[208:209], off
	s_barrier
	s_waitcnt lgkmcnt(0)
	s_setprio 1
	s_waitcnt lgkmcnt(0)
	v_mfma_i32_16x16x64_i8 v[84:87], v[192:195], v[160:163], v[84:87]
	v_mfma_i32_16x16x64_i8 v[56:59], v[200:203], v[160:163], v[56:59]
	v_mfma_i32_16x16x64_i8 v[76:79], v[192:195], v[168:171], v[76:79]
	v_mfma_i32_16x16x64_i8 v[44:47], v[200:203], v[168:171], v[44:47]
	v_mfma_i32_16x16x64_i8 v[64:67], v[192:195], v[176:179], v[64:67]
	v_mfma_i32_16x16x64_i8 v[36:39], v[200:203], v[176:179], v[36:39]
	v_mfma_i32_16x16x64_i8 v[52:55], v[192:195], v[184:187], v[52:55]
	v_mfma_i32_16x16x64_i8 v[28:31], v[200:203], v[184:187], v[28:31]
	v_mfma_i32_16x16x64_i8 v[84:87], v[196:199], v[164:167], v[84:87]
	v_mfma_i32_16x16x64_i8 v[56:59], v[204:207], v[164:167], v[56:59]
	v_mfma_i32_16x16x64_i8 v[76:79], v[196:199], v[172:175], v[76:79]
	v_mfma_i32_16x16x64_i8 v[44:47], v[204:207], v[172:175], v[44:47]
	v_mfma_i32_16x16x64_i8 v[64:67], v[196:199], v[180:183], v[64:67]
	v_mfma_i32_16x16x64_i8 v[36:39], v[204:207], v[180:183], v[36:39]
	v_mfma_i32_16x16x64_i8 v[52:55], v[196:199], v[188:191], v[52:55]
	v_mfma_i32_16x16x64_i8 v[28:31], v[204:207], v[188:191], v[28:31]
	s_setprio 0
	s_mov_b32 m0, s68
	v_lshl_add_u64 v[208:209], v[212:213], 0, s[34:35]
	s_barrier
	ds_read_b128 v[160:163], v232 offset:49152
	ds_read_b128 v[164:167], v232 offset:50176
	ds_read_b128 v[168:171], v232 offset:51200
	ds_read_b128 v[172:175], v232 offset:52224
	ds_read_b128 v[176:179], v232 offset:53248
	ds_read_b128 v[180:183], v232 offset:54272
	ds_read_b128 v[184:187], v232 offset:55296
	ds_read_b128 v[188:191], v232 offset:56320
	global_load_lds_dwordx4 v[208:209], off
	v_lshl_add_u64 v[208:209], v[214:215], 0, s[34:35]
	s_mov_b32 m0, s69
	s_nop 0
	global_load_lds_dwordx4 v[208:209], off
	s_barrier
	s_waitcnt lgkmcnt(0)
	s_setprio 1
	s_waitcnt lgkmcnt(0)
	v_mfma_i32_16x16x64_i8 v[92:95], v[144:147], v[160:163], v[92:95]
	v_mfma_i32_16x16x64_i8 v[72:75], v[152:155], v[160:163], v[72:75]
	v_mfma_i32_16x16x64_i8 v[88:91], v[144:147], v[168:171], v[88:91]
	v_mfma_i32_16x16x64_i8 v[60:63], v[152:155], v[168:171], v[60:63]
	v_mfma_i32_16x16x64_i8 v[80:83], v[144:147], v[176:179], v[80:83]
	v_mfma_i32_16x16x64_i8 v[48:51], v[152:155], v[176:179], v[48:51]
	v_mfma_i32_16x16x64_i8 v[68:71], v[144:147], v[184:187], v[68:71]
	v_mfma_i32_16x16x64_i8 v[40:43], v[152:155], v[184:187], v[40:43]
	v_mfma_i32_16x16x64_i8 v[92:95], v[148:151], v[164:167], v[92:95]
	v_mfma_i32_16x16x64_i8 v[72:75], v[156:159], v[164:167], v[72:75]
	v_mfma_i32_16x16x64_i8 v[88:91], v[148:151], v[172:175], v[88:91]
	v_mfma_i32_16x16x64_i8 v[60:63], v[156:159], v[172:175], v[60:63]
	v_mfma_i32_16x16x64_i8 v[80:83], v[148:151], v[180:183], v[80:83]
	v_mfma_i32_16x16x64_i8 v[48:51], v[156:159], v[180:183], v[48:51]
	v_mfma_i32_16x16x64_i8 v[68:71], v[148:151], v[188:191], v[68:71]
	v_mfma_i32_16x16x64_i8 v[40:43], v[156:159], v[188:191], v[40:43]
	s_setprio 0
	s_barrier
	s_add_u32 s20, s58, 0x20080
	s_addc_u32 s21, s59, 0
	s_add_i32 s56, s57, s19
	v_lshl_add_u64 v[144:145], s[20:21], 0, v[132:133]
	s_mov_b32 m0, s56
	s_nop 0
	global_load_lds_dwordx4 v[144:145], off
	v_lshl_add_u64 v[144:145], s[20:21], 0, v[128:129]
	s_add_i32 m0, s56, 0x2000
	s_nop 0
	global_load_lds_dwordx4 v[144:145], off
	s_waitcnt vmcnt(6)
	s_barrier
	s_setprio 1
	v_mfma_i32_16x16x64_i8 v[32:35], v[192:195], v[160:163], v[32:35]
	v_mfma_i32_16x16x64_i8 v[8:11], v[200:203], v[160:163], v[8:11]
	v_mfma_i32_16x16x64_i8 v[24:27], v[192:195], v[168:171], v[24:27]
	v_mfma_i32_16x16x64_i8 v[12:15], v[200:203], v[168:171], v[12:15]
	v_mfma_i32_16x16x64_i8 v[20:23], v[192:195], v[176:179], v[20:23]
	v_mfma_i32_16x16x64_i8 v[4:7], v[200:203], v[176:179], v[4:7]
	v_mfma_i32_16x16x64_i8 v[16:19], v[192:195], v[184:187], v[16:19]
	v_mfma_i32_16x16x64_i8 v[0:3], v[200:203], v[184:187], v[0:3]
	v_mfma_i32_16x16x64_i8 v[32:35], v[196:199], v[164:167], v[32:35]
	v_mfma_i32_16x16x64_i8 v[8:11], v[204:207], v[164:167], v[8:11]
	v_mfma_i32_16x16x64_i8 v[24:27], v[196:199], v[172:175], v[24:27]
	v_mfma_i32_16x16x64_i8 v[12:15], v[204:207], v[172:175], v[12:15]
	v_mfma_i32_16x16x64_i8 v[20:23], v[196:199], v[180:183], v[20:23]
	v_mfma_i32_16x16x64_i8 v[4:7], v[204:207], v[180:183], v[4:7]
	v_mfma_i32_16x16x64_i8 v[16:19], v[196:199], v[188:191], v[16:19]
	v_mfma_i32_16x16x64_i8 v[0:3], v[204:207], v[188:191], v[0:3]
	s_setprio 0
	s_add_u32 s75, s75, 0x100
	s_addc_u32 s76, s76, 0
	s_cmp_ge_i32 s77, s67
	s_mov_b64 s[56:57], s[8:9]
	s_mov_b32 s58, s77
	s_barrier
	s_cbranch_scc1 .Lpeel_done_P2r

.Lpeel_done_P2r:
	v_cvt_f32_i32_e32 v124, v124
	v_cvt_f32_i32_e32 v125, v125
	v_cvt_f32_i32_e32 v146, v126
	v_cvt_f32_i32_e32 v147, v127
	v_cvt_f32_i32_e32 v120, v120
	v_cvt_f32_i32_e32 v121, v121
	v_cvt_f32_i32_e32 v164, v122
	v_cvt_f32_i32_e32 v165, v123
	v_cvt_f32_i32_e32 v148, v116
	v_cvt_f32_i32_e32 v149, v117
	v_cvt_f32_i32_e32 v166, v118
	v_cvt_f32_i32_e32 v167, v119
	v_cvt_f32_i32_e32 v158, v108
	v_cvt_f32_i32_e32 v159, v109
	v_cvt_f32_i32_e32 v160, v110
	v_cvt_f32_i32_e32 v161, v111
	v_cvt_f32_i32_e32 v162, v92
	v_cvt_f32_i32_e32 v163, v93
	v_cvt_f32_i32_e32 v202, v94
	v_cvt_f32_i32_e32 v203, v95
	v_cvt_f32_i32_e32 v152, v88
	v_cvt_f32_i32_e32 v153, v89
	v_cvt_f32_i32_e32 v154, v90
	v_cvt_f32_i32_e32 v155, v91
	v_cvt_f32_i32_e32 v156, v80
	v_cvt_f32_i32_e32 v157, v81
	v_cvt_f32_i32_e32 v168, v82
	v_cvt_f32_i32_e32 v169, v83
	v_cvt_f32_i32_e32 v206, v68
	v_cvt_f32_i32_e32 v207, v69
	v_cvt_f32_i32_e32 v208, v70
	v_cvt_f32_i32_e32 v209, v71
	v_cvt_f32_i32_e32 v182, v112
	v_cvt_f32_i32_e32 v183, v113
	v_cvt_f32_i32_e32 v188, v114
	v_cvt_f32_i32_e32 v189, v115
	v_cvt_f32_i32_e32 v180, v104
	v_cvt_f32_i32_e32 v181, v105
	v_cvt_f32_i32_e32 v186, v106
	v_cvt_f32_i32_e32 v187, v107
	v_cvt_f32_i32_e32 v178, v100
	v_cvt_f32_i32_e32 v179, v101
	v_cvt_f32_i32_e32 v184, v102
	v_cvt_f32_i32_e32 v185, v103
	v_cvt_f32_i32_e32 v170, v96
	v_cvt_f32_i32_e32 v171, v97
	v_cvt_f32_i32_e32 v172, v98
	v_cvt_f32_i32_e32 v173, v99
	v_cvt_f32_i32_e32 v174, v72
	v_cvt_f32_i32_e32 v175, v73
	v_cvt_f32_i32_e32 v176, v74
	v_cvt_f32_i32_e32 v177, v75
	v_cvt_f32_i32_e32 v190, v60
	v_cvt_f32_i32_e32 v191, v61
	v_cvt_f32_i32_e32 v192, v62
	v_cvt_f32_i32_e32 v193, v63
	v_cvt_f32_i32_e32 v194, v48
	v_cvt_f32_i32_e32 v195, v49
	v_cvt_f32_i32_e32 v196, v50
	v_cvt_f32_i32_e32 v197, v51
	v_cvt_f32_i32_e32 v198, v40
	v_cvt_f32_i32_e32 v199, v41
	v_cvt_f32_i32_e32 v200, v42
	v_cvt_f32_i32_e32 v201, v43
	v_cvt_f32_i32_e32 v94, v84
	v_cvt_f32_i32_e32 v95, v85
	v_cvt_f32_i32_e32 v100, v86
	v_cvt_f32_i32_e32 v101, v87
	v_cvt_f32_i32_e32 v92, v76
	v_cvt_f32_i32_e32 v93, v77
	v_cvt_f32_i32_e32 v98, v78
	v_cvt_f32_i32_e32 v99, v79
	v_cvt_f32_i32_e32 v90, v64
	v_cvt_f32_i32_e32 v91, v65
	v_cvt_f32_i32_e32 v96, v66
	v_cvt_f32_i32_e32 v97, v67
	v_cvt_f32_i32_e32 v82, v52
	v_cvt_f32_i32_e32 v83, v53
	v_cvt_f32_i32_e32 v84, v54
	v_cvt_f32_i32_e32 v85, v55
	v_cvt_f32_i32_e32 v86, v32
	v_cvt_f32_i32_e32 v87, v33
	v_cvt_f32_i32_e32 v88, v34
	v_cvt_f32_i32_e32 v89, v35
	v_cvt_f32_i32_e32 v108, v24
	v_cvt_f32_i32_e32 v109, v25
	v_cvt_f32_i32_e32 v112, v26
	v_cvt_f32_i32_e32 v113, v27
	v_cvt_f32_i32_e32 v114, v20
	v_cvt_f32_i32_e32 v115, v21
	v_cvt_f32_i32_e32 v116, v22
	v_cvt_f32_i32_e32 v117, v23
	v_cvt_f32_i32_e32 v126, v16
	v_cvt_f32_i32_e32 v127, v17
	v_cvt_f32_i32_e32 v144, v18
	v_cvt_f32_i32_e32 v145, v19
	v_cvt_f32_i32_e32 v60, v56
	v_cvt_f32_i32_e32 v61, v57
	v_cvt_f32_i32_e32 v66, v58
	v_cvt_f32_i32_e32 v67, v59
	v_cvt_f32_i32_e32 v56, v44
	v_cvt_f32_i32_e32 v57, v45
	v_cvt_f32_i32_e32 v64, v46
	v_cvt_f32_i32_e32 v65, v47
	v_cvt_f32_i32_e32 v54, v36
	v_cvt_f32_i32_e32 v55, v37
	v_cvt_f32_i32_e32 v62, v38
	v_cvt_f32_i32_e32 v63, v39
	v_cvt_f32_i32_e32 v70, v12
	v_cvt_f32_i32_e32 v71, v13
	v_cvt_f32_i32_e32 v72, v14
	v_cvt_f32_i32_e32 v73, v15
	v_cvt_f32_i32_e32 v74, v4
	v_cvt_f32_i32_e32 v75, v5
	v_cvt_f32_i32_e32 v76, v6
	v_cvt_f32_i32_e32 v77, v7
	v_cvt_f32_i32_e32 v78, v0
	v_cvt_f32_i32_e32 v79, v1
	v_cvt_f32_i32_e32 v80, v2
	v_cvt_f32_i32_e32 v81, v3
	v_cvt_f32_i32_e32 v58, v8
	v_cvt_f32_i32_e32 v59, v9
	v_cvt_f32_i32_e32 v68, v10
	v_cvt_f32_i32_e32 v69, v11
	v_cvt_f32_i32_e32 v50, v28
	v_cvt_f32_i32_e32 v51, v29
	v_cvt_f32_i32_e32 v52, v30
	v_cvt_f32_i32_e32 v53, v31

.LBB0_459:
	s_ashr_i32 s53, s52, 31
	s_lshl_b64 s[20:21], s[52:53], 17
	s_add_u32 s58, s90, s20
	s_addc_u32 s59, s91, s21
	s_andn2_b64 vcc, exec, s[44:45]
	s_cbranch_vccz .Lpz_P4
	v_mov_b32_e32 v139, 0
	v_mov_b32_e32 v138, v139
	v_mov_b32_e32 v137, v139
	v_mov_b32_e32 v136, v139
	v_mov_b32_e32 v127, v139
	v_mov_b32_e32 v126, v139
	v_mov_b32_e32 v125, v139
	v_mov_b32_e32 v124, v139
	v_mov_b32_e32 v119, v139
	v_mov_b32_e32 v118, v139
	v_mov_b32_e32 v117, v139
	v_mov_b32_e32 v116, v139
	v_mov_b32_e32 v107, v139
	v_mov_b32_e32 v106, v139
	v_mov_b32_e32 v105, v139
	v_mov_b32_e32 v104, v139
	v_mov_b32_e32 v99, v139
	v_mov_b32_e32 v98, v139
	v_mov_b32_e32 v97, v139
	v_mov_b32_e32 v96, v139
	v_mov_b32_e32 v87, v139
	v_mov_b32_e32 v86, v139
	v_mov_b32_e32 v85, v139
	v_mov_b32_e32 v84, v139
	v_mov_b32_e32 v79, v139
	v_mov_b32_e32 v78, v139
	v_mov_b32_e32 v77, v139
	v_mov_b32_e32 v76, v139
	v_mov_b32_e32 v71, v139
	v_mov_b32_e32 v70, v139
	v_mov_b32_e32 v69, v139
	v_mov_b32_e32 v68, v139
	v_mov_b32_e32 v131, v139
	v_mov_b32_e32 v130, v139
	v_mov_b32_e32 v129, v139
	v_mov_b32_e32 v128, v139
	v_mov_b32_e32 v123, v139
	v_mov_b32_e32 v122, v139
	v_mov_b32_e32 v121, v139
	v_mov_b32_e32 v120, v139
	v_mov_b32_e32 v111, v139
	v_mov_b32_e32 v110, v139
	v_mov_b32_e32 v109, v139
	v_mov_b32_e32 v108, v139
	v_mov_b32_e32 v103, v139
	v_mov_b32_e32 v102, v139
	v_mov_b32_e32 v101, v139
	v_mov_b32_e32 v100, v139
	v_mov_b32_e32 v91, v139
	v_mov_b32_e32 v90, v139
	v_mov_b32_e32 v89, v139
	v_mov_b32_e32 v88, v139
	v_mov_b32_e32 v83, v139
	v_mov_b32_e32 v82, v139
	v_mov_b32_e32 v81, v139
	v_mov_b32_e32 v80, v139
	v_mov_b32_e32 v75, v139
	v_mov_b32_e32 v74, v139
	v_mov_b32_e32 v73, v139
	v_mov_b32_e32 v72, v139
	v_mov_b32_e32 v67, v139
	v_mov_b32_e32 v66, v139
	v_mov_b32_e32 v65, v139
	v_mov_b32_e32 v64, v139
	v_mov_b32_e32 v63, v139
	v_mov_b32_e32 v62, v139
	v_mov_b32_e32 v61, v139
	v_mov_b32_e32 v60, v139
	v_mov_b32_e32 v55, v139
	v_mov_b32_e32 v54, v139
	v_mov_b32_e32 v53, v139
	v_mov_b32_e32 v52, v139
	v_mov_b32_e32 v47, v139
	v_mov_b32_e32 v46, v139
	v_mov_b32_e32 v45, v139
	v_mov_b32_e32 v44, v139
	v_mov_b32_e32 v39, v139
	v_mov_b32_e32 v38, v139
	v_mov_b32_e32 v37, v139
	v_mov_b32_e32 v36, v139
	v_mov_b32_e32 v31, v139
	v_mov_b32_e32 v30, v139
	v_mov_b32_e32 v29, v139
	v_mov_b32_e32 v28, v139
	v_mov_b32_e32 v23, v139
	v_mov_b32_e32 v22, v139
	v_mov_b32_e32 v21, v139
	v_mov_b32_e32 v20, v139
	v_mov_b32_e32 v15, v139
	v_mov_b32_e32 v14, v139
	v_mov_b32_e32 v13, v139
	v_mov_b32_e32 v12, v139
	v_mov_b32_e32 v7, v139
	v_mov_b32_e32 v6, v139
	v_mov_b32_e32 v5, v139
	v_mov_b32_e32 v4, v139
	v_mov_b32_e32 v59, v139
	v_mov_b32_e32 v58, v139
	v_mov_b32_e32 v57, v139
	v_mov_b32_e32 v56, v139
	v_mov_b32_e32 v51, v139
	v_mov_b32_e32 v50, v139
	v_mov_b32_e32 v49, v139
	v_mov_b32_e32 v48, v139
	v_mov_b32_e32 v43, v139
	v_mov_b32_e32 v42, v139
	v_mov_b32_e32 v41, v139
	v_mov_b32_e32 v40, v139
	v_mov_b32_e32 v35, v139
	v_mov_b32_e32 v34, v139
	v_mov_b32_e32 v33, v139
	v_mov_b32_e32 v32, v139
	v_mov_b32_e32 v27, v139
	v_mov_b32_e32 v26, v139
	v_mov_b32_e32 v25, v139
	v_mov_b32_e32 v24, v139
	v_mov_b32_e32 v19, v139
	v_mov_b32_e32 v18, v139
	v_mov_b32_e32 v17, v139
	v_mov_b32_e32 v16, v139
	v_mov_b32_e32 v11, v139
	v_mov_b32_e32 v10, v139
	v_mov_b32_e32 v9, v139
	v_mov_b32_e32 v8, v139
	v_mov_b32_e32 v3, v139
	v_mov_b32_e32 v2, v139
	v_mov_b32_e32 v1, v139
	v_mov_b32_e32 v0, v139
	s_cbranch_vccnz .LBB0_462
.Lpz_P4:
	s_and_b64 s[4:5], s[4:5], exec
	s_cselect_b32 s53, s59, s9
	s_cselect_b32 s55, s58, s8
	s_add_u32 s64, s8, 0x100
	s_addc_u32 s65, s9, 0
	s_mov_b32 s8, 0
	ds_read_b128 v[92:95], v229
	ds_read_b128 v[112:115], v229 offset:1024
	ds_read_b128 v[132:135], v229 offset:2048
	ds_read_b128 v[140:143], v229 offset:3072
	s_add_i32 s66, s8, 2
	s_add_u32 s4, s6, 0x100
	s_addc_u32 s5, s7, 0
	s_cmp_eq_u32 s19, s8
	s_cselect_b32 s8, s55, s64
	s_cselect_b32 s61, s57, s5
	s_cselect_b32 s60, s56, s4
	s_cselect_b32 s9, s53, s65
	v_lshl_add_u64 v[190:191], s[6:7], 0, v[166:167]
	s_add_i32 m0, s93, 0xc000
	ds_read_b128 v[144:147], v230
	ds_read_b128 v[148:151], v230 offset:1024
	ds_read_b128 v[152:155], v230 offset:2048
	ds_read_b128 v[170:173], v230 offset:3072
	ds_read_b128 v[174:177], v230 offset:4096
	ds_read_b128 v[178:181], v230 offset:5120
	ds_read_b128 v[182:185], v230 offset:6144
	ds_read_b128 v[186:189], v230 offset:7168
	global_load_lds_dwordx4 v[190:191], off
	v_lshl_add_u64 v[190:191], s[6:7], 0, v[168:169]
	s_add_i32 m0, s93, 0xe000
	s_nop 0
	global_load_lds_dwordx4 v[190:191], off
	s_waitcnt lgkmcnt(8)
	s_barrier
	s_waitcnt lgkmcnt(0)
	s_setprio 1
	s_waitcnt lgkmcnt(0)
	v_mfma_f32_16x16x32_bf16 v[136:139], v[92:95], v[144:147], 0
	v_mfma_f32_16x16x32_bf16 v[124:127], v[132:135], v[144:147], 0
	v_mfma_f32_16x16x32_bf16 v[116:119], v[92:95], v[152:155], 0
	v_mfma_f32_16x16x32_bf16 v[104:107], v[132:135], v[152:155], 0
	v_mfma_f32_16x16x32_bf16 v[96:99], v[92:95], v[174:177], 0
	v_mfma_f32_16x16x32_bf16 v[84:87], v[132:135], v[174:177], 0
	v_mfma_f32_16x16x32_bf16 v[76:79], v[92:95], v[182:185], 0
	v_mfma_f32_16x16x32_bf16 v[68:71], v[132:135], v[182:185], 0
	v_mfma_f32_16x16x32_bf16 v[136:139], v[112:115], v[148:151], v[136:139]
	v_mfma_f32_16x16x32_bf16 v[124:127], v[140:143], v[148:151], v[124:127]
	v_mfma_f32_16x16x32_bf16 v[116:119], v[112:115], v[170:173], v[116:119]
	v_mfma_f32_16x16x32_bf16 v[104:107], v[140:143], v[170:173], v[104:107]
	v_mfma_f32_16x16x32_bf16 v[96:99], v[112:115], v[178:181], v[96:99]
	v_mfma_f32_16x16x32_bf16 v[84:87], v[140:143], v[178:181], v[84:87]
	v_mfma_f32_16x16x32_bf16 v[76:79], v[112:115], v[186:189], v[76:79]
	v_mfma_f32_16x16x32_bf16 v[68:71], v[140:143], v[186:189], v[68:71]
	s_setprio 0
	s_barrier
	s_add_i32 s6, s88, s92
	v_lshl_add_u64 v[206:207], s[8:9], 0, v[158:159]
	s_mov_b32 m0, s6
	ds_read_b128 v[190:193], v231
	ds_read_b128 v[194:197], v231 offset:1024
	ds_read_b128 v[198:201], v231 offset:2048
	ds_read_b128 v[202:205], v231 offset:3072
	global_load_lds_dwordx4 v[206:207], off
	v_lshl_add_u64 v[208:209], s[8:9], 0, v[162:163]
	s_add_i32 m0, s6, 0x2000
	s_nop 0
	global_load_lds_dwordx4 v[208:209], off
	s_barrier
	s_waitcnt lgkmcnt(0)
	s_setprio 1
	s_waitcnt lgkmcnt(0)
	v_mfma_f32_16x16x32_bf16 v[128:131], v[190:193], v[144:147], 0
	v_mfma_f32_16x16x32_bf16 v[120:123], v[198:201], v[144:147], 0
	v_mfma_f32_16x16x32_bf16 v[108:111], v[190:193], v[152:155], 0
	v_mfma_f32_16x16x32_bf16 v[100:103], v[198:201], v[152:155], 0
	v_mfma_f32_16x16x32_bf16 v[88:91], v[190:193], v[174:177], 0
	v_mfma_f32_16x16x32_bf16 v[80:83], v[198:201], v[174:177], 0
	v_mfma_f32_16x16x32_bf16 v[72:75], v[190:193], v[182:185], 0
	v_mfma_f32_16x16x32_bf16 v[64:67], v[198:201], v[182:185], 0
	v_mfma_f32_16x16x32_bf16 v[128:131], v[194:197], v[148:151], v[128:131]
	v_mfma_f32_16x16x32_bf16 v[120:123], v[202:205], v[148:151], v[120:123]
	v_mfma_f32_16x16x32_bf16 v[108:111], v[194:197], v[170:173], v[108:111]
	v_mfma_f32_16x16x32_bf16 v[100:103], v[202:205], v[170:173], v[100:103]
	v_mfma_f32_16x16x32_bf16 v[88:91], v[194:197], v[178:181], v[88:91]
	v_mfma_f32_16x16x32_bf16 v[80:83], v[202:205], v[178:181], v[80:83]
	v_mfma_f32_16x16x32_bf16 v[72:75], v[194:197], v[186:189], v[72:75]
	v_mfma_f32_16x16x32_bf16 v[64:67], v[202:205], v[186:189], v[64:67]
	s_setprio 0
	s_mov_b32 m0, s93
	v_lshl_add_u64 v[210:211], s[60:61], 0, v[156:157]
	s_barrier
	ds_read_b128 v[144:147], v230 offset:16384
	ds_read_b128 v[148:151], v230 offset:17408
	ds_read_b128 v[152:155], v230 offset:18432
	ds_read_b128 v[170:173], v230 offset:19456
	ds_read_b128 v[174:177], v230 offset:20480
	ds_read_b128 v[178:181], v230 offset:21504
	ds_read_b128 v[182:185], v230 offset:22528
	ds_read_b128 v[186:189], v230 offset:23552
	global_load_lds_dwordx4 v[210:211], off
	v_lshl_add_u64 v[212:213], s[60:61], 0, v[160:161]
	s_mov_b32 m0, s84
	s_nop 0
	global_load_lds_dwordx4 v[212:213], off
	s_barrier
	s_waitcnt lgkmcnt(0)
	s_setprio 1
	s_waitcnt lgkmcnt(0)
	v_mfma_f32_16x16x32_bf16 v[60:63], v[92:95], v[144:147], 0
	v_mfma_f32_16x16x32_bf16 v[52:55], v[132:135], v[144:147], 0
	v_mfma_f32_16x16x32_bf16 v[44:47], v[92:95], v[152:155], 0
	v_mfma_f32_16x16x32_bf16 v[36:39], v[132:135], v[152:155], 0
	v_mfma_f32_16x16x32_bf16 v[28:31], v[92:95], v[174:177], 0
	v_mfma_f32_16x16x32_bf16 v[20:23], v[132:135], v[174:177], 0
	v_mfma_f32_16x16x32_bf16 v[12:15], v[92:95], v[182:185], 0
	v_mfma_f32_16x16x32_bf16 v[4:7], v[132:135], v[182:185], 0
	v_mfma_f32_16x16x32_bf16 v[60:63], v[112:115], v[148:151], v[60:63]
	v_mfma_f32_16x16x32_bf16 v[52:55], v[140:143], v[148:151], v[52:55]
	v_mfma_f32_16x16x32_bf16 v[44:47], v[112:115], v[170:173], v[44:47]
	v_mfma_f32_16x16x32_bf16 v[36:39], v[140:143], v[170:173], v[36:39]
	v_mfma_f32_16x16x32_bf16 v[28:31], v[112:115], v[178:181], v[28:31]
	v_mfma_f32_16x16x32_bf16 v[20:23], v[140:143], v[178:181], v[20:23]
	v_mfma_f32_16x16x32_bf16 v[12:15], v[112:115], v[186:189], v[12:15]
	v_mfma_f32_16x16x32_bf16 v[4:7], v[140:143], v[186:189], v[4:7]
	s_setprio 0
	s_barrier
	s_add_u32 s6, s8, 0x10000
	s_addc_u32 s7, s9, 0
	s_add_i32 s20, s89, s92
	v_lshl_add_u64 v[92:93], s[6:7], 0, v[158:159]
	s_mov_b32 m0, s20
	s_nop 0
	global_load_lds_dwordx4 v[92:93], off
	v_lshl_add_u64 v[92:93], s[6:7], 0, v[162:163]
	s_add_i32 m0, s20, 0x2000
	s_nop 0
	global_load_lds_dwordx4 v[92:93], off
	s_waitcnt vmcnt(6)
	s_barrier
	s_setprio 1
	v_mfma_f32_16x16x32_bf16 v[56:59], v[190:193], v[144:147], 0
	v_mfma_f32_16x16x32_bf16 v[48:51], v[198:201], v[144:147], 0
	v_mfma_f32_16x16x32_bf16 v[40:43], v[190:193], v[152:155], 0
	v_mfma_f32_16x16x32_bf16 v[32:35], v[198:201], v[152:155], 0
	v_mfma_f32_16x16x32_bf16 v[24:27], v[190:193], v[174:177], 0
	v_mfma_f32_16x16x32_bf16 v[16:19], v[198:201], v[174:177], 0
	v_mfma_f32_16x16x32_bf16 v[8:11], v[190:193], v[182:185], 0
	v_mfma_f32_16x16x32_bf16 v[0:3], v[198:201], v[182:185], 0
	v_mfma_f32_16x16x32_bf16 v[56:59], v[194:197], v[148:151], v[56:59]
	v_mfma_f32_16x16x32_bf16 v[48:51], v[202:205], v[148:151], v[48:51]
	v_mfma_f32_16x16x32_bf16 v[40:43], v[194:197], v[170:173], v[40:43]
	v_mfma_f32_16x16x32_bf16 v[32:35], v[202:205], v[170:173], v[32:35]
	v_mfma_f32_16x16x32_bf16 v[24:27], v[194:197], v[178:181], v[24:27]
	v_mfma_f32_16x16x32_bf16 v[16:19], v[202:205], v[178:181], v[16:19]
	v_mfma_f32_16x16x32_bf16 v[8:11], v[194:197], v[186:189], v[8:11]
	v_mfma_f32_16x16x32_bf16 v[0:3], v[202:205], v[186:189], v[0:3]
	s_setprio 0
	s_add_i32 s20, 0, 0x18000
	v_add_u32_e32 v140, s20, v228
	s_barrier
	ds_read_b128 v[92:95], v140
	ds_read_b128 v[112:115], v140 offset:1024
	ds_read_b128 v[132:135], v140 offset:2048
	ds_read_b128 v[140:143], v140 offset:3072
	s_add_u32 s6, s60, 0x2000
	s_addc_u32 s7, s61, 0
	s_mov_b32 m0, s86
	v_lshl_add_u64 v[190:191], s[6:7], 0, v[156:157]
	ds_read_b128 v[144:147], v230 offset:32768
	ds_read_b128 v[148:151], v230 offset:33792
	ds_read_b128 v[152:155], v230 offset:34816
	ds_read_b128 v[170:173], v230 offset:35840
	ds_read_b128 v[174:177], v230 offset:36864
	ds_read_b128 v[178:181], v230 offset:37888
	ds_read_b128 v[182:185], v230 offset:38912
	ds_read_b128 v[186:189], v230 offset:39936
	global_load_lds_dwordx4 v[190:191], off
	v_lshl_add_u64 v[190:191], s[6:7], 0, v[160:161]
	s_mov_b32 m0, s87
	s_nop 0
	global_load_lds_dwordx4 v[190:191], off
	s_waitcnt lgkmcnt(8)
	s_barrier
	s_waitcnt lgkmcnt(0)
	s_setprio 1
	s_waitcnt lgkmcnt(0)
	v_mfma_f32_16x16x32_bf16 v[136:139], v[92:95], v[144:147], v[136:139]
	v_mfma_f32_16x16x32_bf16 v[124:127], v[132:135], v[144:147], v[124:127]
	v_mfma_f32_16x16x32_bf16 v[116:119], v[92:95], v[152:155], v[116:119]
	v_mfma_f32_16x16x32_bf16 v[104:107], v[132:135], v[152:155], v[104:107]
	v_mfma_f32_16x16x32_bf16 v[96:99], v[92:95], v[174:177], v[96:99]
	v_mfma_f32_16x16x32_bf16 v[84:87], v[132:135], v[174:177], v[84:87]
	v_mfma_f32_16x16x32_bf16 v[76:79], v[92:95], v[182:185], v[76:79]
	v_mfma_f32_16x16x32_bf16 v[68:71], v[132:135], v[182:185], v[68:71]
	v_mfma_f32_16x16x32_bf16 v[136:139], v[112:115], v[148:151], v[136:139]
	v_mfma_f32_16x16x32_bf16 v[124:127], v[140:143], v[148:151], v[124:127]
	v_mfma_f32_16x16x32_bf16 v[116:119], v[112:115], v[170:173], v[116:119]
	v_mfma_f32_16x16x32_bf16 v[104:107], v[140:143], v[170:173], v[104:107]
	v_mfma_f32_16x16x32_bf16 v[96:99], v[112:115], v[178:181], v[96:99]
	v_mfma_f32_16x16x32_bf16 v[84:87], v[140:143], v[178:181], v[84:87]
	v_mfma_f32_16x16x32_bf16 v[76:79], v[112:115], v[186:189], v[76:79]
	v_mfma_f32_16x16x32_bf16 v[68:71], v[140:143], v[186:189], v[68:71]
	s_setprio 0
	s_barrier
	s_add_i32 s21, 0, 0x1c000
	s_add_i32 s6, s20, s92
	v_add_u32_e32 v164, s21, v228
	v_lshl_add_u64 v[206:207], v[206:207], 0, s[42:43]
	s_mov_b32 m0, s6
	ds_read_b128 v[190:193], v164
	ds_read_b128 v[194:197], v164 offset:1024
	ds_read_b128 v[198:201], v164 offset:2048
	ds_read_b128 v[202:205], v164 offset:3072
	global_load_lds_dwordx4 v[206:207], off
	v_lshl_add_u64 v[206:207], v[208:209], 0, s[42:43]
	s_add_i32 m0, s6, 0x2000
	s_nop 0
	global_load_lds_dwordx4 v[206:207], off
	s_barrier
	s_waitcnt lgkmcnt(0)
	s_setprio 1
	s_waitcnt lgkmcnt(0)
	v_mfma_f32_16x16x32_bf16 v[128:131], v[190:193], v[144:147], v[128:131]
	v_mfma_f32_16x16x32_bf16 v[120:123], v[198:201], v[144:147], v[120:123]
	v_mfma_f32_16x16x32_bf16 v[108:111], v[190:193], v[152:155], v[108:111]
	v_mfma_f32_16x16x32_bf16 v[100:103], v[198:201], v[152:155], v[100:103]
	v_mfma_f32_16x16x32_bf16 v[88:91], v[190:193], v[174:177], v[88:91]
	v_mfma_f32_16x16x32_bf16 v[80:83], v[198:201], v[174:177], v[80:83]
	v_mfma_f32_16x16x32_bf16 v[72:75], v[190:193], v[182:185], v[72:75]
	v_mfma_f32_16x16x32_bf16 v[64:67], v[198:201], v[182:185], v[64:67]
	v_mfma_f32_16x16x32_bf16 v[128:131], v[194:197], v[148:151], v[128:131]
	v_mfma_f32_16x16x32_bf16 v[120:123], v[202:205], v[148:151], v[120:123]
	v_mfma_f32_16x16x32_bf16 v[108:111], v[194:197], v[170:173], v[108:111]
	v_mfma_f32_16x16x32_bf16 v[100:103], v[202:205], v[170:173], v[100:103]
	v_mfma_f32_16x16x32_bf16 v[88:91], v[194:197], v[178:181], v[88:91]
	v_mfma_f32_16x16x32_bf16 v[80:83], v[202:205], v[178:181], v[80:83]
	v_mfma_f32_16x16x32_bf16 v[72:75], v[194:197], v[186:189], v[72:75]
	v_mfma_f32_16x16x32_bf16 v[64:67], v[202:205], v[186:189], v[64:67]
	s_setprio 0
	s_mov_b32 m0, s97
	v_lshl_add_u64 v[206:207], v[210:211], 0, s[42:43]
	s_barrier
	ds_read_b128 v[144:147], v230 offset:49152
	ds_read_b128 v[148:151], v230 offset:50176
	ds_read_b128 v[152:155], v230 offset:51200
	ds_read_b128 v[170:173], v230 offset:52224
	ds_read_b128 v[174:177], v230 offset:53248
	ds_read_b128 v[178:181], v230 offset:54272
	ds_read_b128 v[182:185], v230 offset:55296
	ds_read_b128 v[186:189], v230 offset:56320
	global_load_lds_dwordx4 v[206:207], off
	v_lshl_add_u64 v[206:207], v[212:213], 0, s[42:43]
	s_mov_b32 m0, s18
	s_nop 0
	global_load_lds_dwordx4 v[206:207], off
	s_barrier
	s_waitcnt lgkmcnt(0)
	s_setprio 1
	s_waitcnt lgkmcnt(0)
	v_mfma_f32_16x16x32_bf16 v[60:63], v[92:95], v[144:147], v[60:63]
	v_mfma_f32_16x16x32_bf16 v[52:55], v[132:135], v[144:147], v[52:55]
	v_mfma_f32_16x16x32_bf16 v[44:47], v[92:95], v[152:155], v[44:47]
	v_mfma_f32_16x16x32_bf16 v[36:39], v[132:135], v[152:155], v[36:39]
	v_mfma_f32_16x16x32_bf16 v[28:31], v[92:95], v[174:177], v[28:31]
	v_mfma_f32_16x16x32_bf16 v[20:23], v[132:135], v[174:177], v[20:23]
	v_mfma_f32_16x16x32_bf16 v[12:15], v[92:95], v[182:185], v[12:15]
	v_mfma_f32_16x16x32_bf16 v[4:7], v[132:135], v[182:185], v[4:7]
	v_mfma_f32_16x16x32_bf16 v[60:63], v[112:115], v[148:151], v[60:63]
	v_mfma_f32_16x16x32_bf16 v[52:55], v[140:143], v[148:151], v[52:55]
	v_mfma_f32_16x16x32_bf16 v[44:47], v[112:115], v[170:173], v[44:47]
	v_mfma_f32_16x16x32_bf16 v[36:39], v[140:143], v[170:173], v[36:39]
	v_mfma_f32_16x16x32_bf16 v[28:31], v[112:115], v[178:181], v[28:31]
	v_mfma_f32_16x16x32_bf16 v[20:23], v[140:143], v[178:181], v[20:23]
	v_mfma_f32_16x16x32_bf16 v[12:15], v[112:115], v[186:189], v[12:15]
	v_mfma_f32_16x16x32_bf16 v[4:7], v[140:143], v[186:189], v[4:7]
	s_setprio 0
	s_barrier
	s_add_u32 s6, s8, 0x10080
	s_addc_u32 s7, s9, 0
	s_add_i32 s8, s21, s92
	v_lshl_add_u64 v[92:93], s[6:7], 0, v[158:159]
	s_mov_b32 m0, s8
	s_nop 0
	global_load_lds_dwordx4 v[92:93], off
	v_lshl_add_u64 v[92:93], s[6:7], 0, v[162:163]
	s_add_i32 m0, s8, 0x2000
	s_nop 0
	global_load_lds_dwordx4 v[92:93], off
	s_waitcnt vmcnt(6)
	s_barrier
	s_setprio 1
	v_mfma_f32_16x16x32_bf16 v[56:59], v[190:193], v[144:147], v[56:59]
	v_mfma_f32_16x16x32_bf16 v[48:51], v[198:201], v[144:147], v[48:51]
	v_mfma_f32_16x16x32_bf16 v[40:43], v[190:193], v[152:155], v[40:43]
	v_mfma_f32_16x16x32_bf16 v[32:35], v[198:201], v[152:155], v[32:35]
	v_mfma_f32_16x16x32_bf16 v[24:27], v[190:193], v[174:177], v[24:27]
	v_mfma_f32_16x16x32_bf16 v[16:19], v[198:201], v[174:177], v[16:19]
	v_mfma_f32_16x16x32_bf16 v[8:11], v[190:193], v[182:185], v[8:11]
	v_mfma_f32_16x16x32_bf16 v[0:3], v[198:201], v[182:185], v[0:3]
	v_mfma_f32_16x16x32_bf16 v[56:59], v[194:197], v[148:151], v[56:59]
	v_mfma_f32_16x16x32_bf16 v[48:51], v[202:205], v[148:151], v[48:51]
	v_mfma_f32_16x16x32_bf16 v[40:43], v[194:197], v[170:173], v[40:43]
	v_mfma_f32_16x16x32_bf16 v[32:35], v[202:205], v[170:173], v[32:35]
	v_mfma_f32_16x16x32_bf16 v[24:27], v[194:197], v[178:181], v[24:27]
	v_mfma_f32_16x16x32_bf16 v[16:19], v[202:205], v[178:181], v[16:19]
	v_mfma_f32_16x16x32_bf16 v[8:11], v[194:197], v[186:189], v[8:11]
	v_mfma_f32_16x16x32_bf16 v[0:3], v[202:205], v[186:189], v[0:3]
	s_setprio 0
	s_add_u32 s64, s64, 0x100
	s_addc_u32 s65, s65, 0
	s_cmp_lt_i32 s66, s95
	s_mov_b64 s[6:7], s[4:5]
	s_mov_b32 s8, s66
	s_barrier
	s_cbranch_scc0 .Lpeel_done_P4

.Lpeel_done_P4:
.LBB0_462:
	v_cndmask_b32_e64 v92, 0, 1, s[46:47]
	v_cmp_ne_u32_e64 s[4:5], 1, v92
	s_andn2_b64 vcc, exec, s[46:47]
	s_cbranch_vccnz .LBB0_464
	s_barrier

.LBB0_603:
	s_ashr_i32 s59, s58, 31
	s_lshl_b64 s[16:17], s[58:59], 19
	s_add_u32 s60, s55, s16
	s_addc_u32 s61, s70, s17
	s_ashr_i32 s57, s56, 31
	s_lshl_b64 s[16:17], s[56:57], 19
	s_add_u32 s62, s71, s16
	v_cmp_lt_i64_e64 s[12:13], s[12:13], v[168:169]
	s_addc_u32 s63, s72, s17
	s_andn2_b64 vcc, exec, s[46:47]
	s_cbranch_vccz .Lpz_P8
	v_mov_b32_e32 v159, 0
	v_mov_b32_e32 v158, v159
	v_mov_b32_e32 v157, v159
	v_mov_b32_e32 v156, v159
	v_mov_b32_e32 v155, v159
	v_mov_b32_e32 v154, v159
	v_mov_b32_e32 v153, v159
	v_mov_b32_e32 v152, v159
	v_mov_b32_e32 v143, v159
	v_mov_b32_e32 v142, v159
	v_mov_b32_e32 v141, v159
	v_mov_b32_e32 v140, v159
	v_mov_b32_e32 v139, v159
	v_mov_b32_e32 v138, v159
	v_mov_b32_e32 v137, v159
	v_mov_b32_e32 v136, v159
	v_mov_b32_e32 v127, v159
	v_mov_b32_e32 v126, v159
	v_mov_b32_e32 v125, v159
	v_mov_b32_e32 v124, v159
	v_mov_b32_e32 v123, v159
	v_mov_b32_e32 v122, v159
	v_mov_b32_e32 v121, v159
	v_mov_b32_e32 v120, v159
	v_mov_b32_e32 v111, v159
	v_mov_b32_e32 v110, v159
	v_mov_b32_e32 v109, v159
	v_mov_b32_e32 v108, v159
	v_mov_b32_e32 v107, v159
	v_mov_b32_e32 v106, v159
	v_mov_b32_e32 v105, v159
	v_mov_b32_e32 v104, v159
	v_mov_b32_e32 v151, v159
	v_mov_b32_e32 v150, v159
	v_mov_b32_e32 v149, v159
	v_mov_b32_e32 v148, v159
	v_mov_b32_e32 v147, v159
	v_mov_b32_e32 v146, v159
	v_mov_b32_e32 v145, v159
	v_mov_b32_e32 v144, v159
	v_mov_b32_e32 v135, v159
	v_mov_b32_e32 v134, v159
	v_mov_b32_e32 v133, v159
	v_mov_b32_e32 v132, v159
	v_mov_b32_e32 v131, v159
	v_mov_b32_e32 v130, v159
	v_mov_b32_e32 v129, v159
	v_mov_b32_e32 v128, v159
	v_mov_b32_e32 v119, v159
	v_mov_b32_e32 v118, v159
	v_mov_b32_e32 v117, v159
	v_mov_b32_e32 v116, v159
	v_mov_b32_e32 v115, v159
	v_mov_b32_e32 v114, v159
	v_mov_b32_e32 v113, v159
	v_mov_b32_e32 v112, v159
	v_mov_b32_e32 v103, v159
	v_mov_b32_e32 v102, v159
	v_mov_b32_e32 v101, v159
	v_mov_b32_e32 v100, v159
	v_mov_b32_e32 v99, v159
	v_mov_b32_e32 v98, v159
	v_mov_b32_e32 v97, v159
	v_mov_b32_e32 v96, v159
	v_mov_b32_e32 v79, v159
	v_mov_b32_e32 v78, v159
	v_mov_b32_e32 v77, v159
	v_mov_b32_e32 v76, v159
	v_mov_b32_e32 v75, v159
	v_mov_b32_e32 v74, v159
	v_mov_b32_e32 v73, v159
	v_mov_b32_e32 v72, v159
	v_mov_b32_e32 v63, v159
	v_mov_b32_e32 v62, v159
	v_mov_b32_e32 v61, v159
	v_mov_b32_e32 v60, v159
	v_mov_b32_e32 v59, v159
	v_mov_b32_e32 v58, v159
	v_mov_b32_e32 v57, v159
	v_mov_b32_e32 v56, v159
	v_mov_b32_e32 v47, v159
	v_mov_b32_e32 v46, v159
	v_mov_b32_e32 v45, v159
	v_mov_b32_e32 v44, v159
	v_mov_b32_e32 v43, v159
	v_mov_b32_e32 v42, v159
	v_mov_b32_e32 v41, v159
	v_mov_b32_e32 v40, v159
	v_mov_b32_e32 v31, v159
	v_mov_b32_e32 v30, v159
	v_mov_b32_e32 v29, v159
	v_mov_b32_e32 v28, v159
	v_mov_b32_e32 v27, v159
	v_mov_b32_e32 v26, v159
	v_mov_b32_e32 v25, v159
	v_mov_b32_e32 v24, v159
	v_mov_b32_e32 v71, v159
	v_mov_b32_e32 v70, v159
	v_mov_b32_e32 v69, v159
	v_mov_b32_e32 v68, v159
	v_mov_b32_e32 v67, v159
	v_mov_b32_e32 v66, v159
	v_mov_b32_e32 v65, v159
	v_mov_b32_e32 v64, v159
	v_mov_b32_e32 v55, v159
	v_mov_b32_e32 v54, v159
	v_mov_b32_e32 v53, v159
	v_mov_b32_e32 v52, v159
	v_mov_b32_e32 v51, v159
	v_mov_b32_e32 v50, v159
	v_mov_b32_e32 v49, v159
	v_mov_b32_e32 v48, v159
	v_mov_b32_e32 v39, v159
	v_mov_b32_e32 v38, v159
	v_mov_b32_e32 v37, v159
	v_mov_b32_e32 v36, v159
	v_mov_b32_e32 v35, v159
	v_mov_b32_e32 v34, v159
	v_mov_b32_e32 v33, v159
	v_mov_b32_e32 v32, v159
	v_mov_b32_e32 v23, v159
	v_mov_b32_e32 v22, v159
	v_mov_b32_e32 v21, v159
	v_mov_b32_e32 v20, v159
	v_mov_b32_e32 v19, v159
	v_mov_b32_e32 v18, v159
	v_mov_b32_e32 v17, v159
	v_mov_b32_e32 v16, v159
	s_cbranch_vccnz .LBB0_606
.Lpz_P8:
	s_and_b64 s[12:13], s[12:13], exec
	s_cselect_b32 s3, s61, s67
	s_cselect_b32 s15, s60, s66
	s_cselect_b32 s16, s63, s65
	s_cselect_b32 s17, s62, s64
	s_add_u32 s12, s66, 0x40080
	s_addc_u32 s13, s67, 0
	s_add_u32 s18, s64, 0x100
	s_addc_u32 s19, s65, 0
	s_mov_b32 s57, 0
	ds_read_b128 v[0:3], v233
	ds_read_b128 v[4:7], v233 offset:1024
	ds_read_b128 v[8:11], v233 offset:2048
	ds_read_b128 v[12:15], v233 offset:3072
	s_add_i32 s59, s57, 2
	s_add_u32 s20, s12, 0xfffc0080
	s_addc_u32 s21, s13, -1
	s_cmp_eq_u32 s97, s57
	s_cselect_b32 s67, s3, s21
	s_cselect_b32 s66, s15, s20
	s_cselect_b32 s65, s16, s19
	s_cselect_b32 s64, s17, s18
	v_lshl_add_u64 v[190:191], s[12:13], 0, v[164:165]
	s_add_i32 m0, s74, 0xc000
	ds_read_b128 v[80:83], v234
	ds_read_b128 v[84:87], v234 offset:1024
	ds_read_b128 v[88:91], v234 offset:2048
	ds_read_b128 v[92:95], v234 offset:3072
	ds_read_b128 v[174:177], v234 offset:4096
	ds_read_b128 v[178:181], v234 offset:5120
	ds_read_b128 v[182:185], v234 offset:6144
	ds_read_b128 v[186:189], v234 offset:7168
	global_load_lds_dwordx4 v[190:191], off
	v_lshl_add_u64 v[190:191], s[12:13], 0, v[166:167]
	s_add_i32 m0, s74, 0xe000
	s_nop 0
	global_load_lds_dwordx4 v[190:191], off
	s_waitcnt lgkmcnt(8)
	s_barrier
	s_waitcnt lgkmcnt(0)
	s_setprio 1
	s_waitcnt lgkmcnt(0)
	v_mfma_f32_16x16x32_bf16 v[156:159], v[0:3], v[80:83], 0
	v_mfma_f32_16x16x32_bf16 v[152:155], v[8:11], v[80:83], 0
	v_mfma_f32_16x16x32_bf16 v[140:143], v[0:3], v[88:91], 0
	v_mfma_f32_16x16x32_bf16 v[136:139], v[8:11], v[88:91], 0
	v_mfma_f32_16x16x32_bf16 v[124:127], v[0:3], v[174:177], 0
	v_mfma_f32_16x16x32_bf16 v[120:123], v[8:11], v[174:177], 0
	v_mfma_f32_16x16x32_bf16 v[108:111], v[0:3], v[182:185], 0
	v_mfma_f32_16x16x32_bf16 v[104:107], v[8:11], v[182:185], 0
	v_mfma_f32_16x16x32_bf16 v[156:159], v[4:7], v[84:87], v[156:159]
	v_mfma_f32_16x16x32_bf16 v[152:155], v[12:15], v[84:87], v[152:155]
	v_mfma_f32_16x16x32_bf16 v[140:143], v[4:7], v[92:95], v[140:143]
	v_mfma_f32_16x16x32_bf16 v[136:139], v[12:15], v[92:95], v[136:139]
	v_mfma_f32_16x16x32_bf16 v[124:127], v[4:7], v[178:181], v[124:127]
	v_mfma_f32_16x16x32_bf16 v[120:123], v[12:15], v[178:181], v[120:123]
	v_mfma_f32_16x16x32_bf16 v[108:111], v[4:7], v[186:189], v[108:111]
	v_mfma_f32_16x16x32_bf16 v[104:107], v[12:15], v[186:189], v[104:107]
	s_setprio 0
	s_barrier
	s_add_i32 s20, s88, s73
	v_lshl_add_u64 v[214:215], s[64:65], 0, v[160:161]
	s_mov_b32 m0, s20
	ds_read_b128 v[190:193], v235
	ds_read_b128 v[194:197], v235 offset:1024
	ds_read_b128 v[198:201], v235 offset:2048
	ds_read_b128 v[202:205], v235 offset:3072
	global_load_lds_dwordx4 v[214:215], off
	v_lshl_add_u64 v[216:217], s[64:65], 0, v[162:163]
	s_add_i32 m0, s20, 0x2000
	s_nop 0
	global_load_lds_dwordx4 v[216:217], off
	s_barrier
	s_waitcnt lgkmcnt(0)
	s_setprio 1
	s_waitcnt lgkmcnt(0)
	v_mfma_f32_16x16x32_bf16 v[148:151], v[190:193], v[80:83], 0
	v_mfma_f32_16x16x32_bf16 v[80:83], v[198:201], v[80:83], 0
	v_mfma_f32_16x16x32_bf16 v[148:151], v[194:197], v[84:87], v[148:151]
	v_mfma_f32_16x16x32_bf16 v[80:83], v[202:205], v[84:87], v[80:83]
	v_mfma_f32_16x16x32_bf16 v[84:87], v[190:193], v[88:91], 0
	v_mfma_f32_16x16x32_bf16 v[88:91], v[198:201], v[88:91], 0
	v_mfma_f32_16x16x32_bf16 v[112:115], v[198:201], v[174:177], 0
	v_mfma_f32_16x16x32_bf16 v[100:103], v[190:193], v[182:185], 0
	v_mfma_f32_16x16x32_bf16 v[96:99], v[198:201], v[182:185], 0
	v_mfma_f32_16x16x32_bf16 v[84:87], v[194:197], v[92:95], v[84:87]
	v_mfma_f32_16x16x32_bf16 v[88:91], v[202:205], v[92:95], v[88:91]
	v_mfma_f32_16x16x32_bf16 v[92:95], v[190:193], v[174:177], 0
	v_mfma_f32_16x16x32_bf16 v[112:115], v[202:205], v[178:181], v[112:115]
	v_mfma_f32_16x16x32_bf16 v[100:103], v[194:197], v[186:189], v[100:103]
	v_mfma_f32_16x16x32_bf16 v[96:99], v[202:205], v[186:189], v[96:99]
	v_mfma_f32_16x16x32_bf16 v[92:95], v[194:197], v[178:181], v[92:95]
	s_setprio 0
	s_mov_b32 m0, s74
	v_lshl_add_u64 v[218:219], s[66:67], 0, v[160:161]
	s_barrier
	ds_read_b128 v[116:119], v234 offset:16384
	ds_read_b128 v[128:131], v234 offset:17408
	ds_read_b128 v[132:135], v234 offset:18432
	ds_read_b128 v[144:147], v234 offset:19456
	ds_read_b128 v[174:177], v234 offset:20480
	ds_read_b128 v[178:181], v234 offset:21504
	ds_read_b128 v[182:185], v234 offset:22528
	ds_read_b128 v[186:189], v234 offset:23552
	global_load_lds_dwordx4 v[218:219], off
	v_lshl_add_u64 v[220:221], s[66:67], 0, v[162:163]
	s_mov_b32 m0, s75
	s_nop 0
	global_load_lds_dwordx4 v[220:221], off
	s_barrier
	s_waitcnt lgkmcnt(0)
	s_setprio 1
	s_waitcnt lgkmcnt(0)
	v_mfma_f32_16x16x32_bf16 v[76:79], v[0:3], v[116:119], 0
	v_mfma_f32_16x16x32_bf16 v[72:75], v[8:11], v[116:119], 0
	v_mfma_f32_16x16x32_bf16 v[60:63], v[0:3], v[132:135], 0
	v_mfma_f32_16x16x32_bf16 v[56:59], v[8:11], v[132:135], 0
	v_mfma_f32_16x16x32_bf16 v[44:47], v[0:3], v[174:177], 0
	v_mfma_f32_16x16x32_bf16 v[40:43], v[8:11], v[174:177], 0
	v_mfma_f32_16x16x32_bf16 v[0:3], v[0:3], v[182:185], 0
	v_mfma_f32_16x16x32_bf16 v[76:79], v[4:7], v[128:131], v[76:79]
	v_mfma_f32_16x16x32_bf16 v[72:75], v[12:15], v[128:131], v[72:75]
	v_mfma_f32_16x16x32_bf16 v[60:63], v[4:7], v[144:147], v[60:63]
	v_mfma_f32_16x16x32_bf16 v[56:59], v[12:15], v[144:147], v[56:59]
	v_mfma_f32_16x16x32_bf16 v[44:47], v[4:7], v[178:181], v[44:47]
	v_mfma_f32_16x16x32_bf16 v[40:43], v[12:15], v[178:181], v[40:43]
	v_mfma_f32_16x16x32_bf16 v[0:3], v[4:7], v[186:189], v[0:3]
	v_mfma_f32_16x16x32_bf16 v[4:7], v[8:11], v[182:185], 0
	v_mfma_f32_16x16x32_bf16 v[4:7], v[12:15], v[186:189], v[4:7]
	s_setprio 0
	s_barrier
	s_add_u32 s20, s64, 0x40000
	s_addc_u32 s21, s65, 0
	s_add_i32 s57, s89, s73
	v_lshl_add_u64 v[8:9], s[20:21], 0, v[160:161]
	s_mov_b32 m0, s57
	s_nop 0
	global_load_lds_dwordx4 v[8:9], off
	v_lshl_add_u64 v[8:9], s[20:21], 0, v[162:163]
	s_add_i32 m0, s57, 0x2000
	s_nop 0
	global_load_lds_dwordx4 v[8:9], off
	s_waitcnt vmcnt(6)
	s_barrier
	s_setprio 1
	v_mfma_f32_16x16x32_bf16 v[24:27], v[190:193], v[132:135], 0
	v_mfma_f32_16x16x32_bf16 v[52:55], v[194:197], v[144:147], v[24:27]
	v_mfma_f32_16x16x32_bf16 v[24:27], v[198:201], v[132:135], 0
	v_mfma_f32_16x16x32_bf16 v[48:51], v[202:205], v[144:147], v[24:27]
	v_mfma_f32_16x16x32_bf16 v[24:27], v[190:193], v[174:177], 0
	v_mfma_f32_16x16x32_bf16 v[36:39], v[194:197], v[178:181], v[24:27]
	v_mfma_f32_16x16x32_bf16 v[24:27], v[198:201], v[174:177], 0
	v_mfma_f32_16x16x32_bf16 v[20:23], v[190:193], v[182:185], 0
	v_mfma_f32_16x16x32_bf16 v[16:19], v[198:201], v[182:185], 0
	v_mfma_f32_16x16x32_bf16 v[8:11], v[190:193], v[116:119], 0
	v_mfma_f32_16x16x32_bf16 v[12:15], v[198:201], v[116:119], 0
	v_mfma_f32_16x16x32_bf16 v[32:35], v[202:205], v[178:181], v[24:27]
	v_mfma_f32_16x16x32_bf16 v[20:23], v[194:197], v[186:189], v[20:23]
	v_mfma_f32_16x16x32_bf16 v[16:19], v[202:205], v[186:189], v[16:19]
	v_mfma_f32_16x16x32_bf16 v[8:11], v[194:197], v[128:131], v[8:11]
	v_mfma_f32_16x16x32_bf16 v[12:15], v[202:205], v[128:131], v[12:15]
	s_setprio 0
	s_add_i32 s57, 0, 0x18000
	v_add_u32_e32 v68, s57, v228
	s_barrier
	ds_read_b128 v[24:27], v68
	ds_read_b128 v[28:31], v68 offset:1024
	ds_read_b128 v[64:67], v68 offset:2048
	ds_read_b128 v[68:71], v68 offset:3072
	s_add_u32 s20, s66, 0x40000
	s_addc_u32 s21, s67, 0
	s_mov_b32 m0, s76
	v_lshl_add_u64 v[132:133], s[20:21], 0, v[160:161]
	ds_read_b128 v[116:119], v234 offset:32768
	ds_read_b128 v[128:131], v234 offset:33792
	ds_read_b128 v[174:177], v234 offset:34816
	ds_read_b128 v[178:181], v234 offset:35840
	ds_read_b128 v[182:185], v234 offset:36864
	ds_read_b128 v[186:189], v234 offset:37888
	ds_read_b128 v[190:193], v234 offset:38912
	ds_read_b128 v[194:197], v234 offset:39936
	global_load_lds_dwordx4 v[132:133], off
	v_lshl_add_u64 v[132:133], s[20:21], 0, v[162:163]
	s_mov_b32 m0, s77
	s_nop 0
	global_load_lds_dwordx4 v[132:133], off
	s_waitcnt lgkmcnt(8)
	s_barrier
	s_waitcnt lgkmcnt(0)
	s_setprio 1
	s_waitcnt lgkmcnt(0)
	v_mfma_f32_16x16x32_bf16 v[132:135], v[24:27], v[116:119], v[156:159]
	v_mfma_f32_16x16x32_bf16 v[156:159], v[28:31], v[128:131], v[132:135]
	v_mfma_f32_16x16x32_bf16 v[132:135], v[64:67], v[116:119], v[152:155]
	v_mfma_f32_16x16x32_bf16 v[152:155], v[68:71], v[128:131], v[132:135]
	v_mfma_f32_16x16x32_bf16 v[132:135], v[24:27], v[174:177], v[140:143]
	v_mfma_f32_16x16x32_bf16 v[140:143], v[28:31], v[178:181], v[132:135]
	v_mfma_f32_16x16x32_bf16 v[132:135], v[64:67], v[174:177], v[136:139]
	v_mfma_f32_16x16x32_bf16 v[124:127], v[24:27], v[182:185], v[124:127]
	v_mfma_f32_16x16x32_bf16 v[120:123], v[64:67], v[182:185], v[120:123]
	v_mfma_f32_16x16x32_bf16 v[108:111], v[24:27], v[190:193], v[108:111]
	v_mfma_f32_16x16x32_bf16 v[104:107], v[64:67], v[190:193], v[104:107]
	v_mfma_f32_16x16x32_bf16 v[136:139], v[68:71], v[178:181], v[132:135]
	v_mfma_f32_16x16x32_bf16 v[124:127], v[28:31], v[186:189], v[124:127]
	v_mfma_f32_16x16x32_bf16 v[120:123], v[68:71], v[186:189], v[120:123]
	v_mfma_f32_16x16x32_bf16 v[108:111], v[28:31], v[194:197], v[108:111]
	v_mfma_f32_16x16x32_bf16 v[104:107], v[68:71], v[194:197], v[104:107]
	s_setprio 0
	s_barrier
	s_add_i32 s66, 0, 0x1c000
	v_add_u32_e32 v132, s66, v228
	s_add_i32 s20, s57, s73
	ds_read_b128 v[198:201], v132
	ds_read_b128 v[202:205], v132 offset:1024
	ds_read_b128 v[206:209], v132 offset:2048
	ds_read_b128 v[210:213], v132 offset:3072
	v_lshl_add_u64 v[132:133], v[214:215], 0, s[44:45]
	s_mov_b32 m0, s20
	s_nop 0
	global_load_lds_dwordx4 v[132:133], off
	v_lshl_add_u64 v[132:133], v[216:217], 0, s[44:45]
	s_add_i32 m0, s20, 0x2000
	s_nop 0
	global_load_lds_dwordx4 v[132:133], off
	s_barrier
	s_waitcnt lgkmcnt(0)
	s_setprio 1
	s_waitcnt lgkmcnt(0)
	v_mfma_f32_16x16x32_bf16 v[80:83], v[206:209], v[116:119], v[80:83]
	v_mfma_f32_16x16x32_bf16 v[132:135], v[198:201], v[116:119], v[148:151]
	v_mfma_f32_16x16x32_bf16 v[144:147], v[210:213], v[128:131], v[80:83]
	v_mfma_f32_16x16x32_bf16 v[80:83], v[198:201], v[174:177], v[84:87]
	v_mfma_f32_16x16x32_bf16 v[148:151], v[202:205], v[128:131], v[132:135]
	v_mfma_f32_16x16x32_bf16 v[132:135], v[202:205], v[178:181], v[80:83]
	v_mfma_f32_16x16x32_bf16 v[80:83], v[206:209], v[174:177], v[88:91]
	v_mfma_f32_16x16x32_bf16 v[128:131], v[210:213], v[178:181], v[80:83]
	v_mfma_f32_16x16x32_bf16 v[80:83], v[198:201], v[182:185], v[92:95]
	v_mfma_f32_16x16x32_bf16 v[116:119], v[202:205], v[186:189], v[80:83]
	v_mfma_f32_16x16x32_bf16 v[80:83], v[206:209], v[182:185], v[112:115]
	v_mfma_f32_16x16x32_bf16 v[112:115], v[210:213], v[186:189], v[80:83]
	v_mfma_f32_16x16x32_bf16 v[80:83], v[198:201], v[190:193], v[100:103]
	v_mfma_f32_16x16x32_bf16 v[100:103], v[202:205], v[194:197], v[80:83]
	v_mfma_f32_16x16x32_bf16 v[80:83], v[206:209], v[190:193], v[96:99]
	v_mfma_f32_16x16x32_bf16 v[96:99], v[210:213], v[194:197], v[80:83]
	s_setprio 0
	s_mov_b32 m0, s95
	v_lshl_add_u64 v[190:191], v[218:219], 0, s[44:45]
	s_barrier
	s_nop 2
	ds_read_b128 v[80:83], v234 offset:49152
	ds_read_b128 v[84:87], v234 offset:50176
	ds_read_b128 v[88:91], v234 offset:51200
	ds_read_b128 v[92:95], v234 offset:52224
	ds_read_b128 v[174:177], v234 offset:53248
	ds_read_b128 v[178:181], v234 offset:54272
	ds_read_b128 v[182:185], v234 offset:55296
	ds_read_b128 v[186:189], v234 offset:56320
	global_load_lds_dwordx4 v[190:191], off
	v_lshl_add_u64 v[190:191], v[220:221], 0, s[44:45]
	s_mov_b32 m0, s96
	s_nop 0
	global_load_lds_dwordx4 v[190:191], off
	s_barrier
	s_waitcnt lgkmcnt(0)
	s_setprio 1
	s_waitcnt lgkmcnt(0)
	v_mfma_f32_16x16x32_bf16 v[76:79], v[24:27], v[80:83], v[76:79]
	v_mfma_f32_16x16x32_bf16 v[60:63], v[24:27], v[88:91], v[60:63]
	v_mfma_f32_16x16x32_bf16 v[44:47], v[24:27], v[174:177], v[44:47]
	v_mfma_f32_16x16x32_bf16 v[0:3], v[24:27], v[182:185], v[0:3]
	v_mfma_f32_16x16x32_bf16 v[76:79], v[28:31], v[84:87], v[76:79]
	v_mfma_f32_16x16x32_bf16 v[72:75], v[64:67], v[80:83], v[72:75]
	v_mfma_f32_16x16x32_bf16 v[60:63], v[28:31], v[92:95], v[60:63]
	v_mfma_f32_16x16x32_bf16 v[56:59], v[64:67], v[88:91], v[56:59]
	v_mfma_f32_16x16x32_bf16 v[44:47], v[28:31], v[178:181], v[44:47]
	v_mfma_f32_16x16x32_bf16 v[40:43], v[64:67], v[174:177], v[40:43]
	v_mfma_f32_16x16x32_bf16 v[28:31], v[28:31], v[186:189], v[0:3]
	v_mfma_f32_16x16x32_bf16 v[0:3], v[64:67], v[182:185], v[4:7]
	v_mfma_f32_16x16x32_bf16 v[72:75], v[68:71], v[84:87], v[72:75]
	v_mfma_f32_16x16x32_bf16 v[56:59], v[68:71], v[92:95], v[56:59]
	v_mfma_f32_16x16x32_bf16 v[40:43], v[68:71], v[178:181], v[40:43]
	v_mfma_f32_16x16x32_bf16 v[24:27], v[68:71], v[186:189], v[0:3]
	s_setprio 0
	s_barrier
	s_add_u32 s20, s64, 0x40080
	s_addc_u32 s21, s65, 0
	s_add_i32 s57, s66, s73
	v_lshl_add_u64 v[0:1], s[20:21], 0, v[160:161]
	s_mov_b32 m0, s57
	s_nop 0
	global_load_lds_dwordx4 v[0:1], off
	v_lshl_add_u64 v[0:1], s[20:21], 0, v[162:163]
	s_add_i32 m0, s57, 0x2000
	s_nop 0
	global_load_lds_dwordx4 v[0:1], off
	s_waitcnt vmcnt(6)
	s_barrier
	s_setprio 1
	v_mfma_f32_16x16x32_bf16 v[0:3], v[198:201], v[80:83], v[8:11]
	v_mfma_f32_16x16x32_bf16 v[68:71], v[202:205], v[84:87], v[0:3]
	v_mfma_f32_16x16x32_bf16 v[0:3], v[206:209], v[80:83], v[12:15]
	v_mfma_f32_16x16x32_bf16 v[64:67], v[210:213], v[84:87], v[0:3]
	v_mfma_f32_16x16x32_bf16 v[0:3], v[198:201], v[88:91], v[52:55]
	v_mfma_f32_16x16x32_bf16 v[52:55], v[202:205], v[92:95], v[0:3]
	v_mfma_f32_16x16x32_bf16 v[0:3], v[206:209], v[88:91], v[48:51]
	v_mfma_f32_16x16x32_bf16 v[48:51], v[210:213], v[92:95], v[0:3]
	v_mfma_f32_16x16x32_bf16 v[0:3], v[198:201], v[174:177], v[36:39]
	v_mfma_f32_16x16x32_bf16 v[36:39], v[202:205], v[178:181], v[0:3]
	v_mfma_f32_16x16x32_bf16 v[0:3], v[206:209], v[174:177], v[32:35]
	v_mfma_f32_16x16x32_bf16 v[32:35], v[210:213], v[178:181], v[0:3]
	v_mfma_f32_16x16x32_bf16 v[0:3], v[198:201], v[182:185], v[20:23]
	v_mfma_f32_16x16x32_bf16 v[20:23], v[202:205], v[186:189], v[0:3]
	v_mfma_f32_16x16x32_bf16 v[0:3], v[206:209], v[182:185], v[16:19]
	v_mfma_f32_16x16x32_bf16 v[16:19], v[210:213], v[186:189], v[0:3]
	s_setprio 0
	s_add_u32 s12, s12, 0x100
	s_addc_u32 s13, s13, 0
	s_add_u32 s18, s18, 0x100
	s_addc_u32 s19, s19, 0
	s_cmp_lt_i32 s59, s93
	s_mov_b32 s57, s59
	s_barrier
	s_cbranch_scc0 .Lpeel_done_P8

.Lpeel_done_P8:
.LBB0_606:
	v_cndmask_b32_e64 v0, 0, 1, s[48:49]
	v_cmp_ne_u32_e64 s[12:13], 1, v0
	s_andn2_b64 vcc, exec, s[48:49]
	s_cbranch_vccnz .LBB0_608
	s_barrier

.Lzskip_P10:
	v_cmp_lt_i64_e32 vcc, s[46:47], v[136:137]
	s_and_b64 s[20:21], vcc, exec
	s_cselect_b32 s31, s37, s43
	s_cselect_b32 s35, s36, s42
	s_cselect_b32 s58, s39, s45
	s_cselect_b32 s59, s38, s44
	s_add_u32 s42, s42, 0x20080
	s_addc_u32 s43, s43, 0
	s_add_u32 s60, s44, 0x100
	s_addc_u32 s61, s45, 0
	s_mov_b32 s44, 0
	v_add_u32_e32 v152, s88, v167
	ds_read_b128 v[140:143], v152
	ds_read_b128 v[144:147], v152 offset:1024
	ds_read_b128 v[148:151], v152 offset:2048
	ds_read_b128 v[152:155], v152 offset:3072
	s_add_i32 s62, s44, 2
	s_add_u32 s20, s42, 0xfffe0080
	s_addc_u32 s21, s43, -1
	s_cmp_eq_u32 s55, s44
	s_cselect_b32 s44, s59, s60
	s_cselect_b32 s47, s31, s21
	s_cselect_b32 s46, s35, s20
	s_cselect_b32 s45, s58, s61
	v_lshl_add_u64 v[198:199], s[42:43], 0, v[132:133]
	s_add_i32 m0, s41, 0xc000
	ds_read_b128 v[156:159], v172
	ds_read_b128 v[160:163], v172 offset:1024
	ds_read_b128 v[174:177], v172 offset:2048
	ds_read_b128 v[178:181], v172 offset:3072
	ds_read_b128 v[182:185], v172 offset:4096
	ds_read_b128 v[186:189], v172 offset:5120
	ds_read_b128 v[190:193], v172 offset:6144
	ds_read_b128 v[194:197], v172 offset:7168
	global_load_lds_dwordx4 v[198:199], off
	v_lshl_add_u64 v[198:199], s[42:43], 0, v[134:135]
	s_add_i32 m0, s41, 0xe000
	s_nop 0
	global_load_lds_dwordx4 v[198:199], off
	s_waitcnt lgkmcnt(8)
	s_barrier
	s_waitcnt lgkmcnt(0)
	s_setprio 1
	s_waitcnt lgkmcnt(0)
	v_mfma_i32_16x16x64_i8 v[124:127], v[140:143], v[156:159], 0
	v_mfma_i32_16x16x64_i8 v[120:123], v[148:151], v[156:159], 0
	v_mfma_i32_16x16x64_i8 v[116:119], v[140:143], v[174:177], 0
	v_mfma_i32_16x16x64_i8 v[112:115], v[148:151], v[174:177], 0
	v_mfma_i32_16x16x64_i8 v[108:111], v[140:143], v[182:185], 0
	v_mfma_i32_16x16x64_i8 v[104:107], v[148:151], v[182:185], 0
	v_mfma_i32_16x16x64_i8 v[100:103], v[140:143], v[190:193], 0
	v_mfma_i32_16x16x64_i8 v[96:99], v[148:151], v[190:193], 0
	v_mfma_i32_16x16x64_i8 v[124:127], v[144:147], v[160:163], v[124:127]
	v_mfma_i32_16x16x64_i8 v[120:123], v[152:155], v[160:163], v[120:123]
	v_mfma_i32_16x16x64_i8 v[116:119], v[144:147], v[178:181], v[116:119]
	v_mfma_i32_16x16x64_i8 v[112:115], v[152:155], v[178:181], v[112:115]
	v_mfma_i32_16x16x64_i8 v[108:111], v[144:147], v[186:189], v[108:111]
	v_mfma_i32_16x16x64_i8 v[104:107], v[152:155], v[186:189], v[104:107]
	v_mfma_i32_16x16x64_i8 v[100:103], v[144:147], v[194:197], v[100:103]
	v_mfma_i32_16x16x64_i8 v[96:99], v[152:155], v[194:197], v[96:99]
	s_setprio 0
	s_barrier
	s_add_i32 s20, s88, s18
	v_add_u32_e32 v164, s89, v167
	v_lshl_add_u64 v[214:215], s[44:45], 0, v[130:131]
	s_mov_b32 m0, s20
	ds_read_b128 v[198:201], v164
	ds_read_b128 v[202:205], v164 offset:1024
	ds_read_b128 v[206:209], v164 offset:2048
	ds_read_b128 v[210:213], v164 offset:3072
	global_load_lds_dwordx4 v[214:215], off
	v_lshl_add_u64 v[216:217], s[44:45], 0, v[128:129]
	s_add_i32 m0, s20, 0x2000
	s_nop 0
	global_load_lds_dwordx4 v[216:217], off
	s_barrier
	s_waitcnt lgkmcnt(0)
	s_setprio 1
	s_waitcnt lgkmcnt(0)
	v_mfma_i32_16x16x64_i8 v[92:95], v[198:201], v[156:159], 0
	v_mfma_i32_16x16x64_i8 v[88:91], v[206:209], v[156:159], 0
	v_mfma_i32_16x16x64_i8 v[84:87], v[198:201], v[174:177], 0
	v_mfma_i32_16x16x64_i8 v[80:83], v[206:209], v[174:177], 0
	v_mfma_i32_16x16x64_i8 v[76:79], v[198:201], v[182:185], 0
	v_mfma_i32_16x16x64_i8 v[72:75], v[206:209], v[182:185], 0
	v_mfma_i32_16x16x64_i8 v[68:71], v[198:201], v[190:193], 0
	v_mfma_i32_16x16x64_i8 v[64:67], v[206:209], v[190:193], 0
	v_mfma_i32_16x16x64_i8 v[92:95], v[202:205], v[160:163], v[92:95]
	v_mfma_i32_16x16x64_i8 v[88:91], v[210:213], v[160:163], v[88:91]
	v_mfma_i32_16x16x64_i8 v[84:87], v[202:205], v[178:181], v[84:87]
	v_mfma_i32_16x16x64_i8 v[80:83], v[210:213], v[178:181], v[80:83]
	v_mfma_i32_16x16x64_i8 v[76:79], v[202:205], v[186:189], v[76:79]
	v_mfma_i32_16x16x64_i8 v[72:75], v[210:213], v[186:189], v[72:75]
	v_mfma_i32_16x16x64_i8 v[68:71], v[202:205], v[194:197], v[68:71]
	v_mfma_i32_16x16x64_i8 v[64:67], v[210:213], v[194:197], v[64:67]
	s_setprio 0
	s_mov_b32 m0, s41
	v_lshl_add_u64 v[218:219], s[46:47], 0, v[130:131]
	s_barrier
	ds_read_b128 v[156:159], v172 offset:16384
	ds_read_b128 v[160:163], v172 offset:17408
	ds_read_b128 v[174:177], v172 offset:18432
	ds_read_b128 v[178:181], v172 offset:19456
	ds_read_b128 v[182:185], v172 offset:20480
	ds_read_b128 v[186:189], v172 offset:21504
	ds_read_b128 v[190:193], v172 offset:22528
	ds_read_b128 v[194:197], v172 offset:23552
	global_load_lds_dwordx4 v[218:219], off
	v_lshl_add_u64 v[220:221], s[46:47], 0, v[128:129]
	s_mov_b32 m0, s48
	s_nop 0
	global_load_lds_dwordx4 v[220:221], off
	s_barrier
	s_waitcnt lgkmcnt(0)
	s_setprio 1
	s_waitcnt lgkmcnt(0)
	v_mfma_i32_16x16x64_i8 v[60:63], v[140:143], v[156:159], 0
	v_mfma_i32_16x16x64_i8 v[56:59], v[148:151], v[156:159], 0
	v_mfma_i32_16x16x64_i8 v[52:55], v[140:143], v[174:177], 0
	v_mfma_i32_16x16x64_i8 v[48:51], v[148:151], v[174:177], 0
	v_mfma_i32_16x16x64_i8 v[44:47], v[140:143], v[182:185], 0
	v_mfma_i32_16x16x64_i8 v[40:43], v[148:151], v[182:185], 0
	v_mfma_i32_16x16x64_i8 v[36:39], v[140:143], v[190:193], 0
	v_mfma_i32_16x16x64_i8 v[32:35], v[148:151], v[190:193], 0
	v_mfma_i32_16x16x64_i8 v[60:63], v[144:147], v[160:163], v[60:63]
	v_mfma_i32_16x16x64_i8 v[56:59], v[152:155], v[160:163], v[56:59]
	v_mfma_i32_16x16x64_i8 v[52:55], v[144:147], v[178:181], v[52:55]
	v_mfma_i32_16x16x64_i8 v[48:51], v[152:155], v[178:181], v[48:51]
	v_mfma_i32_16x16x64_i8 v[44:47], v[144:147], v[186:189], v[44:47]
	v_mfma_i32_16x16x64_i8 v[40:43], v[152:155], v[186:189], v[40:43]
	v_mfma_i32_16x16x64_i8 v[36:39], v[144:147], v[194:197], v[36:39]
	v_mfma_i32_16x16x64_i8 v[32:35], v[152:155], v[194:197], v[32:35]
	s_setprio 0
	s_barrier
	s_add_u32 s20, s44, 0x20000
	s_addc_u32 s21, s45, 0
	s_add_i32 s63, s89, s18
	v_lshl_add_u64 v[140:141], s[20:21], 0, v[130:131]
	s_mov_b32 m0, s63
	s_nop 0
	global_load_lds_dwordx4 v[140:141], off
	v_lshl_add_u64 v[140:141], s[20:21], 0, v[128:129]
	s_add_i32 m0, s63, 0x2000
	s_nop 0
	global_load_lds_dwordx4 v[140:141], off
	s_waitcnt vmcnt(6)
	s_barrier
	s_setprio 1
	v_mfma_i32_16x16x64_i8 v[28:31], v[198:201], v[156:159], 0
	v_mfma_i32_16x16x64_i8 v[24:27], v[206:209], v[156:159], 0
	v_mfma_i32_16x16x64_i8 v[20:23], v[198:201], v[174:177], 0
	v_mfma_i32_16x16x64_i8 v[16:19], v[206:209], v[174:177], 0
	v_mfma_i32_16x16x64_i8 v[12:15], v[198:201], v[182:185], 0
	v_mfma_i32_16x16x64_i8 v[8:11], v[206:209], v[182:185], 0
	v_mfma_i32_16x16x64_i8 v[4:7], v[198:201], v[190:193], 0
	v_mfma_i32_16x16x64_i8 v[0:3], v[206:209], v[190:193], 0
	v_mfma_i32_16x16x64_i8 v[28:31], v[202:205], v[160:163], v[28:31]
	v_mfma_i32_16x16x64_i8 v[24:27], v[210:213], v[160:163], v[24:27]
	v_mfma_i32_16x16x64_i8 v[20:23], v[202:205], v[178:181], v[20:23]
	v_mfma_i32_16x16x64_i8 v[16:19], v[210:213], v[178:181], v[16:19]
	v_mfma_i32_16x16x64_i8 v[12:15], v[202:205], v[186:189], v[12:15]
	v_mfma_i32_16x16x64_i8 v[8:11], v[210:213], v[186:189], v[8:11]
	v_mfma_i32_16x16x64_i8 v[4:7], v[202:205], v[194:197], v[4:7]
	v_mfma_i32_16x16x64_i8 v[0:3], v[210:213], v[194:197], v[0:3]
	s_setprio 0
	s_add_i32 s63, 0, 0x18000
	v_add_u32_e32 v152, s63, v167
	s_barrier
	ds_read_b128 v[140:143], v152
	ds_read_b128 v[144:147], v152 offset:1024
	ds_read_b128 v[148:151], v152 offset:2048
	ds_read_b128 v[152:155], v152 offset:3072
	s_add_u32 s20, s46, 0x20000
	s_addc_u32 s21, s47, 0
	s_mov_b32 m0, s49
	v_lshl_add_u64 v[198:199], s[20:21], 0, v[130:131]
	ds_read_b128 v[156:159], v172 offset:32768
	ds_read_b128 v[160:163], v172 offset:33792
	ds_read_b128 v[174:177], v172 offset:34816
	ds_read_b128 v[178:181], v172 offset:35840
	ds_read_b128 v[182:185], v172 offset:36864
	ds_read_b128 v[186:189], v172 offset:37888
	ds_read_b128 v[190:193], v172 offset:38912
	ds_read_b128 v[194:197], v172 offset:39936
	global_load_lds_dwordx4 v[198:199], off
	v_lshl_add_u64 v[198:199], s[20:21], 0, v[128:129]
	s_mov_b32 m0, s50
	s_nop 0
	global_load_lds_dwordx4 v[198:199], off
	s_waitcnt lgkmcnt(8)
	s_barrier
	s_waitcnt lgkmcnt(0)
	s_setprio 1
	s_waitcnt lgkmcnt(0)
	v_mfma_i32_16x16x64_i8 v[124:127], v[140:143], v[156:159], v[124:127]
	v_mfma_i32_16x16x64_i8 v[120:123], v[148:151], v[156:159], v[120:123]
	v_mfma_i32_16x16x64_i8 v[116:119], v[140:143], v[174:177], v[116:119]
	v_mfma_i32_16x16x64_i8 v[112:115], v[148:151], v[174:177], v[112:115]
	v_mfma_i32_16x16x64_i8 v[108:111], v[140:143], v[182:185], v[108:111]
	v_mfma_i32_16x16x64_i8 v[104:107], v[148:151], v[182:185], v[104:107]
	v_mfma_i32_16x16x64_i8 v[100:103], v[140:143], v[190:193], v[100:103]
	v_mfma_i32_16x16x64_i8 v[96:99], v[148:151], v[190:193], v[96:99]
	v_mfma_i32_16x16x64_i8 v[124:127], v[144:147], v[160:163], v[124:127]
	v_mfma_i32_16x16x64_i8 v[120:123], v[152:155], v[160:163], v[120:123]
	v_mfma_i32_16x16x64_i8 v[116:119], v[144:147], v[178:181], v[116:119]
	v_mfma_i32_16x16x64_i8 v[112:115], v[152:155], v[178:181], v[112:115]
	v_mfma_i32_16x16x64_i8 v[108:111], v[144:147], v[186:189], v[108:111]
	v_mfma_i32_16x16x64_i8 v[104:107], v[152:155], v[186:189], v[104:107]
	v_mfma_i32_16x16x64_i8 v[100:103], v[144:147], v[194:197], v[100:103]
	v_mfma_i32_16x16x64_i8 v[96:99], v[152:155], v[194:197], v[96:99]
	s_setprio 0
	s_barrier
	s_add_i32 s46, 0, 0x1c000
	s_add_i32 s20, s63, s18
	v_add_u32_e32 v164, s46, v167
	v_lshl_add_u64 v[214:215], v[214:215], 0, s[26:27]
	s_mov_b32 m0, s20
	ds_read_b128 v[198:201], v164
	ds_read_b128 v[202:205], v164 offset:1024
	ds_read_b128 v[206:209], v164 offset:2048
	ds_read_b128 v[210:213], v164 offset:3072
	global_load_lds_dwordx4 v[214:215], off
	v_lshl_add_u64 v[214:215], v[216:217], 0, s[26:27]
	s_add_i32 m0, s20, 0x2000
	s_nop 0
	global_load_lds_dwordx4 v[214:215], off
	s_barrier
	s_waitcnt lgkmcnt(0)
	s_setprio 1
	s_waitcnt lgkmcnt(0)
	v_mfma_i32_16x16x64_i8 v[92:95], v[198:201], v[156:159], v[92:95]
	v_mfma_i32_16x16x64_i8 v[88:91], v[206:209], v[156:159], v[88:91]
	v_mfma_i32_16x16x64_i8 v[84:87], v[198:201], v[174:177], v[84:87]
	v_mfma_i32_16x16x64_i8 v[80:83], v[206:209], v[174:177], v[80:83]
	v_mfma_i32_16x16x64_i8 v[76:79], v[198:201], v[182:185], v[76:79]
	v_mfma_i32_16x16x64_i8 v[72:75], v[206:209], v[182:185], v[72:75]
	v_mfma_i32_16x16x64_i8 v[68:71], v[198:201], v[190:193], v[68:71]
	v_mfma_i32_16x16x64_i8 v[64:67], v[206:209], v[190:193], v[64:67]
	v_mfma_i32_16x16x64_i8 v[92:95], v[202:205], v[160:163], v[92:95]
	v_mfma_i32_16x16x64_i8 v[88:91], v[210:213], v[160:163], v[88:91]
	v_mfma_i32_16x16x64_i8 v[84:87], v[202:205], v[178:181], v[84:87]
	v_mfma_i32_16x16x64_i8 v[80:83], v[210:213], v[178:181], v[80:83]
	v_mfma_i32_16x16x64_i8 v[76:79], v[202:205], v[186:189], v[76:79]
	v_mfma_i32_16x16x64_i8 v[72:75], v[210:213], v[186:189], v[72:75]
	v_mfma_i32_16x16x64_i8 v[68:71], v[202:205], v[194:197], v[68:71]
	v_mfma_i32_16x16x64_i8 v[64:67], v[210:213], v[194:197], v[64:67]
	s_setprio 0
	s_mov_b32 m0, s53
	v_lshl_add_u64 v[214:215], v[218:219], 0, s[26:27]
	s_barrier
	ds_read_b128 v[156:159], v172 offset:49152
	ds_read_b128 v[160:163], v172 offset:50176
	ds_read_b128 v[174:177], v172 offset:51200
	ds_read_b128 v[178:181], v172 offset:52224
	ds_read_b128 v[182:185], v172 offset:53248
	ds_read_b128 v[186:189], v172 offset:54272
	ds_read_b128 v[190:193], v172 offset:55296
	ds_read_b128 v[194:197], v172 offset:56320
	global_load_lds_dwordx4 v[214:215], off
	v_lshl_add_u64 v[214:215], v[220:221], 0, s[26:27]
	s_mov_b32 m0, s54
	s_nop 0
	global_load_lds_dwordx4 v[214:215], off
	s_barrier
	s_waitcnt lgkmcnt(0)
	s_setprio 1
	s_waitcnt lgkmcnt(0)
	v_mfma_i32_16x16x64_i8 v[60:63], v[140:143], v[156:159], v[60:63]
	v_mfma_i32_16x16x64_i8 v[56:59], v[148:151], v[156:159], v[56:59]
	v_mfma_i32_16x16x64_i8 v[52:55], v[140:143], v[174:177], v[52:55]
	v_mfma_i32_16x16x64_i8 v[48:51], v[148:151], v[174:177], v[48:51]
	v_mfma_i32_16x16x64_i8 v[44:47], v[140:143], v[182:185], v[44:47]
	v_mfma_i32_16x16x64_i8 v[40:43], v[148:151], v[182:185], v[40:43]
	v_mfma_i32_16x16x64_i8 v[36:39], v[140:143], v[190:193], v[36:39]
	v_mfma_i32_16x16x64_i8 v[32:35], v[148:151], v[190:193], v[32:35]
	v_mfma_i32_16x16x64_i8 v[60:63], v[144:147], v[160:163], v[60:63]
	v_mfma_i32_16x16x64_i8 v[56:59], v[152:155], v[160:163], v[56:59]
	v_mfma_i32_16x16x64_i8 v[52:55], v[144:147], v[178:181], v[52:55]
	v_mfma_i32_16x16x64_i8 v[48:51], v[152:155], v[178:181], v[48:51]
	v_mfma_i32_16x16x64_i8 v[44:47], v[144:147], v[186:189], v[44:47]
	v_mfma_i32_16x16x64_i8 v[40:43], v[152:155], v[186:189], v[40:43]
	v_mfma_i32_16x16x64_i8 v[36:39], v[144:147], v[194:197], v[36:39]
	v_mfma_i32_16x16x64_i8 v[32:35], v[152:155], v[194:197], v[32:35]
	s_setprio 0
	s_barrier
	s_add_u32 s20, s44, 0x20080
	s_addc_u32 s21, s45, 0
	s_add_i32 s44, s46, s18
	v_lshl_add_u64 v[140:141], s[20:21], 0, v[130:131]
	s_mov_b32 m0, s44
	s_nop 0
	global_load_lds_dwordx4 v[140:141], off
	v_lshl_add_u64 v[140:141], s[20:21], 0, v[128:129]
	s_add_i32 m0, s44, 0x2000
	s_nop 0
	global_load_lds_dwordx4 v[140:141], off
	s_waitcnt vmcnt(6)
	s_barrier
	s_setprio 1
	v_mfma_i32_16x16x64_i8 v[28:31], v[198:201], v[156:159], v[28:31]
	v_mfma_i32_16x16x64_i8 v[24:27], v[206:209], v[156:159], v[24:27]
	v_mfma_i32_16x16x64_i8 v[20:23], v[198:201], v[174:177], v[20:23]
	v_mfma_i32_16x16x64_i8 v[16:19], v[206:209], v[174:177], v[16:19]
	v_mfma_i32_16x16x64_i8 v[12:15], v[198:201], v[182:185], v[12:15]
	v_mfma_i32_16x16x64_i8 v[8:11], v[206:209], v[182:185], v[8:11]
	v_mfma_i32_16x16x64_i8 v[4:7], v[198:201], v[190:193], v[4:7]
	v_mfma_i32_16x16x64_i8 v[0:3], v[206:209], v[190:193], v[0:3]
	v_mfma_i32_16x16x64_i8 v[28:31], v[202:205], v[160:163], v[28:31]
	v_mfma_i32_16x16x64_i8 v[24:27], v[210:213], v[160:163], v[24:27]
	v_mfma_i32_16x16x64_i8 v[20:23], v[202:205], v[178:181], v[20:23]
	v_mfma_i32_16x16x64_i8 v[16:19], v[210:213], v[178:181], v[16:19]
	v_mfma_i32_16x16x64_i8 v[12:15], v[202:205], v[186:189], v[12:15]
	v_mfma_i32_16x16x64_i8 v[8:11], v[210:213], v[186:189], v[8:11]
	v_mfma_i32_16x16x64_i8 v[4:7], v[202:205], v[194:197], v[4:7]
	v_mfma_i32_16x16x64_i8 v[0:3], v[210:213], v[194:197], v[0:3]
	s_setprio 0
	s_add_u32 s42, s42, 0x100
	s_addc_u32 s43, s43, 0
	s_add_u32 s60, s60, 0x100
	s_addc_u32 s61, s61, 0
	s_cmp_ge_i32 s62, s52
	s_mov_b32 s44, s62
	s_barrier
	s_cbranch_scc1 .Lpeel_done_P10

.Lpeel_done_P10:
	v_cvt_f32_i32_e32 v160, v124
	v_cvt_f32_i32_e32 v161, v125
	v_cvt_f32_i32_e32 v162, v126
	v_cvt_f32_i32_e32 v163, v127
	v_cvt_f32_i32_e32 v146, v120
	v_cvt_f32_i32_e32 v147, v121
	v_cvt_f32_i32_e32 v158, v122
	v_cvt_f32_i32_e32 v159, v123
	v_cvt_f32_i32_e32 v144, v116
	v_cvt_f32_i32_e32 v145, v117
	v_cvt_f32_i32_e32 v156, v118
	v_cvt_f32_i32_e32 v157, v119
	v_cvt_f32_i32_e32 v140, v112
	v_cvt_f32_i32_e32 v141, v113
	v_cvt_f32_i32_e32 v154, v114
	v_cvt_f32_i32_e32 v155, v115
	v_cvt_f32_i32_e32 v126, v108
	v_cvt_f32_i32_e32 v127, v109
	v_cvt_f32_i32_e32 v152, v110
	v_cvt_f32_i32_e32 v153, v111
	v_cvt_f32_i32_e32 v124, v104
	v_cvt_f32_i32_e32 v125, v105
	v_cvt_f32_i32_e32 v150, v106
	v_cvt_f32_i32_e32 v151, v107
	v_cvt_f32_i32_e32 v122, v100
	v_cvt_f32_i32_e32 v123, v101
	v_cvt_f32_i32_e32 v148, v102
	v_cvt_f32_i32_e32 v149, v103
	v_cvt_f32_i32_e32 v118, v96
	v_cvt_f32_i32_e32 v119, v97
	v_cvt_f32_i32_e32 v142, v98
	v_cvt_f32_i32_e32 v143, v99
	v_cvt_f32_i32_e32 v100, v92
	v_cvt_f32_i32_e32 v101, v93
	v_cvt_f32_i32_e32 v120, v94
	v_cvt_f32_i32_e32 v121, v95
	v_cvt_f32_i32_e32 v98, v88
	v_cvt_f32_i32_e32 v99, v89
	v_cvt_f32_i32_e32 v116, v90
	v_cvt_f32_i32_e32 v117, v91
	v_cvt_f32_i32_e32 v96, v84
	v_cvt_f32_i32_e32 v97, v85
	v_cvt_f32_i32_e32 v114, v86
	v_cvt_f32_i32_e32 v115, v87
	v_cvt_f32_i32_e32 v94, v80
	v_cvt_f32_i32_e32 v95, v81
	v_cvt_f32_i32_e32 v112, v82
	v_cvt_f32_i32_e32 v113, v83
	v_cvt_f32_i32_e32 v92, v76
	v_cvt_f32_i32_e32 v93, v77
	v_cvt_f32_i32_e32 v110, v78
	v_cvt_f32_i32_e32 v111, v79
	v_cvt_f32_i32_e32 v90, v72
	v_cvt_f32_i32_e32 v91, v73
	v_cvt_f32_i32_e32 v108, v74
	v_cvt_f32_i32_e32 v109, v75
	v_cvt_f32_i32_e32 v88, v68
	v_cvt_f32_i32_e32 v89, v69
	v_cvt_f32_i32_e32 v106, v70
	v_cvt_f32_i32_e32 v107, v71
	v_cvt_f32_i32_e32 v86, v64
	v_cvt_f32_i32_e32 v87, v65
	v_cvt_f32_i32_e32 v104, v66
	v_cvt_f32_i32_e32 v105, v67
	v_cvt_f32_i32_e32 v84, v60
	v_cvt_f32_i32_e32 v85, v61
	v_cvt_f32_i32_e32 v102, v62
	v_cvt_f32_i32_e32 v103, v63
	v_cvt_f32_i32_e32 v72, v56
	v_cvt_f32_i32_e32 v73, v57
	v_cvt_f32_i32_e32 v82, v58
	v_cvt_f32_i32_e32 v83, v59
	v_cvt_f32_i32_e32 v70, v52
	v_cvt_f32_i32_e32 v71, v53
	v_cvt_f32_i32_e32 v80, v54
	v_cvt_f32_i32_e32 v81, v55
	v_cvt_f32_i32_e32 v52, v48
	v_cvt_f32_i32_e32 v53, v49
	v_cvt_f32_i32_e32 v78, v50
	v_cvt_f32_i32_e32 v79, v51
	v_cvt_f32_i32_e32 v48, v44
	v_cvt_f32_i32_e32 v49, v45
	v_cvt_f32_i32_e32 v46, v46
	v_cvt_f32_i32_e32 v47, v47
	v_cvt_f32_i32_e32 v44, v40
	v_cvt_f32_i32_e32 v45, v41
	v_cvt_f32_i32_e32 v76, v42
	v_cvt_f32_i32_e32 v77, v43
	v_cvt_f32_i32_e32 v42, v36
	v_cvt_f32_i32_e32 v43, v37
	v_cvt_f32_i32_e32 v74, v38
	v_cvt_f32_i32_e32 v75, v39
	v_cvt_f32_i32_e32 v40, v32
	v_cvt_f32_i32_e32 v41, v33
	v_cvt_f32_i32_e32 v68, v34
	v_cvt_f32_i32_e32 v69, v35
	v_cvt_f32_i32_e32 v38, v28
	v_cvt_f32_i32_e32 v39, v29
	v_cvt_f32_i32_e32 v66, v30
	v_cvt_f32_i32_e32 v67, v31
	v_cvt_f32_i32_e32 v36, v24
	v_cvt_f32_i32_e32 v37, v25
	v_cvt_f32_i32_e32 v64, v26
	v_cvt_f32_i32_e32 v65, v27
	v_cvt_f32_i32_e32 v34, v20
	v_cvt_f32_i32_e32 v35, v21
	v_cvt_f32_i32_e32 v62, v22
	v_cvt_f32_i32_e32 v63, v23
	v_cvt_f32_i32_e32 v32, v16
	v_cvt_f32_i32_e32 v33, v17
	v_cvt_f32_i32_e32 v60, v18
	v_cvt_f32_i32_e32 v61, v19
	v_cvt_f32_i32_e32 v30, v12
	v_cvt_f32_i32_e32 v31, v13
	v_cvt_f32_i32_e32 v58, v14
	v_cvt_f32_i32_e32 v59, v15
	v_cvt_f32_i32_e32 v28, v8
	v_cvt_f32_i32_e32 v29, v9
	v_cvt_f32_i32_e32 v56, v10
	v_cvt_f32_i32_e32 v57, v11
	v_cvt_f32_i32_e32 v26, v4
	v_cvt_f32_i32_e32 v27, v5
	v_cvt_f32_i32_e32 v54, v6
	v_cvt_f32_i32_e32 v55, v7
	v_cvt_f32_i32_e32 v24, v0
	v_cvt_f32_i32_e32 v25, v1
	v_cvt_f32_i32_e32 v50, v2
	v_cvt_f32_i32_e32 v51, v3

.LBB0_796:
	s_andn2_b64 vcc, exec, s[38:39]
	s_cbranch_vccz .Lpz_P11
	v_mov_b32_e32 v139, 0
	v_mov_b32_e32 v138, v139
	v_mov_b32_e32 v137, v139
	v_mov_b32_e32 v136, v139
	v_mov_b32_e32 v143, v139
	v_mov_b32_e32 v142, v139
	v_mov_b32_e32 v141, v139
	v_mov_b32_e32 v140, v139
	v_mov_b32_e32 v127, v139
	v_mov_b32_e32 v126, v139
	v_mov_b32_e32 v125, v139
	v_mov_b32_e32 v124, v139
	v_mov_b32_e32 v123, v139
	v_mov_b32_e32 v122, v139
	v_mov_b32_e32 v121, v139
	v_mov_b32_e32 v120, v139
	v_mov_b32_e32 v111, v139
	v_mov_b32_e32 v110, v139
	v_mov_b32_e32 v109, v139
	v_mov_b32_e32 v108, v139
	v_mov_b32_e32 v107, v139
	v_mov_b32_e32 v106, v139
	v_mov_b32_e32 v105, v139
	v_mov_b32_e32 v104, v139
	v_mov_b32_e32 v95, v139
	v_mov_b32_e32 v94, v139
	v_mov_b32_e32 v93, v139
	v_mov_b32_e32 v92, v139
	v_mov_b32_e32 v91, v139
	v_mov_b32_e32 v90, v139
	v_mov_b32_e32 v89, v139
	v_mov_b32_e32 v88, v139
	v_mov_b32_e32 v135, v139
	v_mov_b32_e32 v134, v139
	v_mov_b32_e32 v133, v139
	v_mov_b32_e32 v132, v139
	v_mov_b32_e32 v131, v139
	v_mov_b32_e32 v130, v139
	v_mov_b32_e32 v129, v139
	v_mov_b32_e32 v128, v139
	v_mov_b32_e32 v119, v139
	v_mov_b32_e32 v118, v139
	v_mov_b32_e32 v117, v139
	v_mov_b32_e32 v116, v139
	v_mov_b32_e32 v115, v139
	v_mov_b32_e32 v114, v139
	v_mov_b32_e32 v113, v139
	v_mov_b32_e32 v112, v139
	v_mov_b32_e32 v103, v139
	v_mov_b32_e32 v102, v139
	v_mov_b32_e32 v101, v139
	v_mov_b32_e32 v100, v139
	v_mov_b32_e32 v99, v139
	v_mov_b32_e32 v98, v139
	v_mov_b32_e32 v97, v139
	v_mov_b32_e32 v96, v139
	v_mov_b32_e32 v87, v139
	v_mov_b32_e32 v86, v139
	v_mov_b32_e32 v85, v139
	v_mov_b32_e32 v84, v139
	v_mov_b32_e32 v83, v139
	v_mov_b32_e32 v82, v139
	v_mov_b32_e32 v81, v139
	v_mov_b32_e32 v80, v139
	v_mov_b32_e32 v67, v139
	v_mov_b32_e32 v66, v139
	v_mov_b32_e32 v65, v139
	v_mov_b32_e32 v64, v139
	v_mov_b32_e32 v63, v139
	v_mov_b32_e32 v62, v139
	v_mov_b32_e32 v61, v139
	v_mov_b32_e32 v60, v139
	v_mov_b32_e32 v47, v139
	v_mov_b32_e32 v46, v139
	v_mov_b32_e32 v45, v139
	v_mov_b32_e32 v44, v139
	v_mov_b32_e32 v43, v139
	v_mov_b32_e32 v42, v139
	v_mov_b32_e32 v41, v139
	v_mov_b32_e32 v40, v139
	v_mov_b32_e32 v31, v139
	v_mov_b32_e32 v30, v139
	v_mov_b32_e32 v29, v139
	v_mov_b32_e32 v28, v139
	v_mov_b32_e32 v27, v139
	v_mov_b32_e32 v26, v139
	v_mov_b32_e32 v25, v139
	v_mov_b32_e32 v24, v139
	v_mov_b32_e32 v15, v139
	v_mov_b32_e32 v14, v139
	v_mov_b32_e32 v13, v139
	v_mov_b32_e32 v12, v139
	v_mov_b32_e32 v11, v139
	v_mov_b32_e32 v10, v139
	v_mov_b32_e32 v9, v139
	v_mov_b32_e32 v8, v139
	v_mov_b32_e32 v55, v139
	v_mov_b32_e32 v54, v139
	v_mov_b32_e32 v53, v139
	v_mov_b32_e32 v52, v139
	v_mov_b32_e32 v51, v139
	v_mov_b32_e32 v50, v139
	v_mov_b32_e32 v49, v139
	v_mov_b32_e32 v48, v139
	v_mov_b32_e32 v39, v139
	v_mov_b32_e32 v38, v139
	v_mov_b32_e32 v37, v139
	v_mov_b32_e32 v36, v139
	v_mov_b32_e32 v35, v139
	v_mov_b32_e32 v34, v139
	v_mov_b32_e32 v33, v139
	v_mov_b32_e32 v32, v139
	v_mov_b32_e32 v23, v139
	v_mov_b32_e32 v22, v139
	v_mov_b32_e32 v21, v139
	v_mov_b32_e32 v20, v139
	v_mov_b32_e32 v19, v139
	v_mov_b32_e32 v18, v139
	v_mov_b32_e32 v17, v139
	v_mov_b32_e32 v16, v139
	v_mov_b32_e32 v7, v139
	v_mov_b32_e32 v6, v139
	v_mov_b32_e32 v5, v139
	v_mov_b32_e32 v4, v139
	v_mov_b32_e32 v3, v139
	v_mov_b32_e32 v2, v139
	v_mov_b32_e32 v1, v139
	v_mov_b32_e32 v0, v139
	s_cbranch_vccnz .LBB0_799
.Lpz_P11:
	s_add_u32 s14, s12, 0x100
	s_addc_u32 s15, s13, 0
	s_mov_b32 s8, 0
	ds_read_b128 v[56:59], v181
	ds_read_b128 v[68:71], v181 offset:1024
	ds_read_b128 v[72:75], v181 offset:2048
	ds_read_b128 v[76:79], v181 offset:3072
	s_add_i32 s16, s8, 2
	s_add_u32 s6, s10, 0x100
	s_addc_u32 s7, s11, 0
	s_cmp_eq_u32 s66, s8
	s_cselect_b32 s8, s48, s14
	s_cselect_b32 s13, s47, s7
	s_cselect_b32 s12, s46, s6
	s_cselect_b32 s9, s49, s15
	v_lshl_add_u64 v[196:197], s[10:11], 0, v[164:165]
	s_add_i32 m0, s53, 0xc000
	ds_read_b128 v[144:147], v182
	ds_read_b128 v[148:151], v182 offset:1024
	ds_read_b128 v[152:155], v182 offset:2048
	ds_read_b128 v[156:159], v182 offset:3072
	ds_read_b128 v[172:175], v182 offset:4096
	ds_read_b128 v[184:187], v182 offset:5120
	ds_read_b128 v[188:191], v182 offset:6144
	ds_read_b128 v[192:195], v182 offset:7168
	global_load_lds_dwordx4 v[196:197], off
	v_lshl_add_u64 v[196:197], s[10:11], 0, v[166:167]
	s_add_i32 m0, s53, 0xe000
	s_nop 0
	global_load_lds_dwordx4 v[196:197], off
	s_waitcnt lgkmcnt(8)
	s_barrier
	s_waitcnt lgkmcnt(0)
	s_setprio 1
	s_waitcnt lgkmcnt(0)
	v_mfma_f32_16x16x32_bf16 v[136:139], v[56:59], v[144:147], 0
	v_mfma_f32_16x16x32_bf16 v[140:143], v[72:75], v[144:147], 0
	v_mfma_f32_16x16x32_bf16 v[124:127], v[56:59], v[152:155], 0
	v_mfma_f32_16x16x32_bf16 v[120:123], v[72:75], v[152:155], 0
	v_mfma_f32_16x16x32_bf16 v[108:111], v[56:59], v[172:175], 0
	v_mfma_f32_16x16x32_bf16 v[104:107], v[72:75], v[172:175], 0
	v_mfma_f32_16x16x32_bf16 v[92:95], v[56:59], v[188:191], 0
	v_mfma_f32_16x16x32_bf16 v[88:91], v[72:75], v[188:191], 0
	v_mfma_f32_16x16x32_bf16 v[136:139], v[68:71], v[148:151], v[136:139]
	v_mfma_f32_16x16x32_bf16 v[140:143], v[76:79], v[148:151], v[140:143]
	v_mfma_f32_16x16x32_bf16 v[124:127], v[68:71], v[156:159], v[124:127]
	v_mfma_f32_16x16x32_bf16 v[120:123], v[76:79], v[156:159], v[120:123]
	v_mfma_f32_16x16x32_bf16 v[108:111], v[68:71], v[184:187], v[108:111]
	v_mfma_f32_16x16x32_bf16 v[104:107], v[76:79], v[184:187], v[104:107]
	v_mfma_f32_16x16x32_bf16 v[92:95], v[68:71], v[192:195], v[92:95]
	v_mfma_f32_16x16x32_bf16 v[88:91], v[76:79], v[192:195], v[88:91]
	s_setprio 0
	s_barrier
	s_add_i32 s10, s88, s52
	v_lshl_add_u64 v[212:213], s[8:9], 0, v[160:161]
	s_mov_b32 m0, s10
	ds_read_b128 v[196:199], v183
	ds_read_b128 v[200:203], v183 offset:1024
	ds_read_b128 v[204:207], v183 offset:2048
	ds_read_b128 v[208:211], v183 offset:3072
	global_load_lds_dwordx4 v[212:213], off
	v_lshl_add_u64 v[214:215], s[8:9], 0, v[162:163]
	s_add_i32 m0, s10, 0x2000
	s_nop 0
	global_load_lds_dwordx4 v[214:215], off
	s_barrier
	s_waitcnt lgkmcnt(0)
	s_setprio 1
	s_waitcnt lgkmcnt(0)
	v_mfma_f32_16x16x32_bf16 v[132:135], v[196:199], v[144:147], 0
	v_mfma_f32_16x16x32_bf16 v[128:131], v[204:207], v[144:147], 0
	v_mfma_f32_16x16x32_bf16 v[116:119], v[196:199], v[152:155], 0
	v_mfma_f32_16x16x32_bf16 v[112:115], v[204:207], v[152:155], 0
	v_mfma_f32_16x16x32_bf16 v[100:103], v[196:199], v[172:175], 0
	v_mfma_f32_16x16x32_bf16 v[96:99], v[204:207], v[172:175], 0
	v_mfma_f32_16x16x32_bf16 v[84:87], v[196:199], v[188:191], 0
	v_mfma_f32_16x16x32_bf16 v[80:83], v[204:207], v[188:191], 0
	v_mfma_f32_16x16x32_bf16 v[132:135], v[200:203], v[148:151], v[132:135]
	v_mfma_f32_16x16x32_bf16 v[128:131], v[208:211], v[148:151], v[128:131]
	v_mfma_f32_16x16x32_bf16 v[116:119], v[200:203], v[156:159], v[116:119]
	v_mfma_f32_16x16x32_bf16 v[112:115], v[208:211], v[156:159], v[112:115]
	v_mfma_f32_16x16x32_bf16 v[100:103], v[200:203], v[184:187], v[100:103]
	v_mfma_f32_16x16x32_bf16 v[96:99], v[208:211], v[184:187], v[96:99]
	v_mfma_f32_16x16x32_bf16 v[84:87], v[200:203], v[192:195], v[84:87]
	v_mfma_f32_16x16x32_bf16 v[80:83], v[208:211], v[192:195], v[80:83]
	s_setprio 0
	s_mov_b32 m0, s53
	v_lshl_add_u64 v[216:217], s[12:13], 0, v[160:161]
	s_barrier
	ds_read_b128 v[144:147], v182 offset:16384
	ds_read_b128 v[148:151], v182 offset:17408
	ds_read_b128 v[152:155], v182 offset:18432
	ds_read_b128 v[156:159], v182 offset:19456
	ds_read_b128 v[172:175], v182 offset:20480
	ds_read_b128 v[184:187], v182 offset:21504
	ds_read_b128 v[188:191], v182 offset:22528
	ds_read_b128 v[192:195], v182 offset:23552
	global_load_lds_dwordx4 v[216:217], off
	v_lshl_add_u64 v[218:219], s[12:13], 0, v[162:163]
	s_mov_b32 m0, s54
	s_nop 0
	global_load_lds_dwordx4 v[218:219], off
	s_barrier
	s_waitcnt lgkmcnt(0)
	s_setprio 1
	s_waitcnt lgkmcnt(0)
	v_mfma_f32_16x16x32_bf16 v[64:67], v[56:59], v[144:147], 0
	v_mfma_f32_16x16x32_bf16 v[60:63], v[72:75], v[144:147], 0
	v_mfma_f32_16x16x32_bf16 v[44:47], v[56:59], v[152:155], 0
	v_mfma_f32_16x16x32_bf16 v[40:43], v[72:75], v[152:155], 0
	v_mfma_f32_16x16x32_bf16 v[28:31], v[56:59], v[172:175], 0
	v_mfma_f32_16x16x32_bf16 v[24:27], v[72:75], v[172:175], 0
	v_mfma_f32_16x16x32_bf16 v[12:15], v[56:59], v[188:191], 0
	v_mfma_f32_16x16x32_bf16 v[8:11], v[72:75], v[188:191], 0
	v_mfma_f32_16x16x32_bf16 v[64:67], v[68:71], v[148:151], v[64:67]
	v_mfma_f32_16x16x32_bf16 v[60:63], v[76:79], v[148:151], v[60:63]
	v_mfma_f32_16x16x32_bf16 v[44:47], v[68:71], v[156:159], v[44:47]
	v_mfma_f32_16x16x32_bf16 v[40:43], v[76:79], v[156:159], v[40:43]
	v_mfma_f32_16x16x32_bf16 v[28:31], v[68:71], v[184:187], v[28:31]
	v_mfma_f32_16x16x32_bf16 v[24:27], v[76:79], v[184:187], v[24:27]
	v_mfma_f32_16x16x32_bf16 v[12:15], v[68:71], v[192:195], v[12:15]
	v_mfma_f32_16x16x32_bf16 v[8:11], v[76:79], v[192:195], v[8:11]
	s_setprio 0
	s_barrier
	s_add_u32 s10, s8, 0xb0000
	s_addc_u32 s11, s9, 0
	s_add_i32 s17, s89, s52
	v_lshl_add_u64 v[56:57], s[10:11], 0, v[160:161]
	s_mov_b32 m0, s17
	s_nop 0
	global_load_lds_dwordx4 v[56:57], off
	v_lshl_add_u64 v[56:57], s[10:11], 0, v[162:163]
	s_add_i32 m0, s17, 0x2000
	s_nop 0
	global_load_lds_dwordx4 v[56:57], off
	s_waitcnt vmcnt(6)
	s_barrier
	s_setprio 1
	v_mfma_f32_16x16x32_bf16 v[52:55], v[196:199], v[144:147], 0
	v_mfma_f32_16x16x32_bf16 v[48:51], v[204:207], v[144:147], 0
	v_mfma_f32_16x16x32_bf16 v[36:39], v[196:199], v[152:155], 0
	v_mfma_f32_16x16x32_bf16 v[32:35], v[204:207], v[152:155], 0
	v_mfma_f32_16x16x32_bf16 v[20:23], v[196:199], v[172:175], 0
	v_mfma_f32_16x16x32_bf16 v[16:19], v[204:207], v[172:175], 0
	v_mfma_f32_16x16x32_bf16 v[4:7], v[196:199], v[188:191], 0
	v_mfma_f32_16x16x32_bf16 v[0:3], v[204:207], v[188:191], 0
	v_mfma_f32_16x16x32_bf16 v[52:55], v[200:203], v[148:151], v[52:55]
	v_mfma_f32_16x16x32_bf16 v[48:51], v[208:211], v[148:151], v[48:51]
	v_mfma_f32_16x16x32_bf16 v[36:39], v[200:203], v[156:159], v[36:39]
	v_mfma_f32_16x16x32_bf16 v[32:35], v[208:211], v[156:159], v[32:35]
	v_mfma_f32_16x16x32_bf16 v[20:23], v[200:203], v[184:187], v[20:23]
	v_mfma_f32_16x16x32_bf16 v[16:19], v[208:211], v[184:187], v[16:19]
	v_mfma_f32_16x16x32_bf16 v[4:7], v[200:203], v[192:195], v[4:7]
	v_mfma_f32_16x16x32_bf16 v[0:3], v[208:211], v[192:195], v[0:3]
	s_setprio 0
	s_add_i32 s17, 0, 0x18000
	v_add_u32_e32 v76, s17, v177
	s_barrier
	ds_read_b128 v[56:59], v76
	ds_read_b128 v[68:71], v76 offset:1024
	ds_read_b128 v[72:75], v76 offset:2048
	ds_read_b128 v[76:79], v76 offset:3072
	s_add_u32 s10, s12, 0xb0000
	s_addc_u32 s11, s13, 0
	s_mov_b32 m0, s55
	v_lshl_add_u64 v[196:197], s[10:11], 0, v[160:161]
	ds_read_b128 v[144:147], v182 offset:32768
	ds_read_b128 v[148:151], v182 offset:33792
	ds_read_b128 v[152:155], v182 offset:34816
	ds_read_b128 v[156:159], v182 offset:35840
	ds_read_b128 v[172:175], v182 offset:36864
	ds_read_b128 v[184:187], v182 offset:37888
	ds_read_b128 v[188:191], v182 offset:38912
	ds_read_b128 v[192:195], v182 offset:39936
	global_load_lds_dwordx4 v[196:197], off
	v_lshl_add_u64 v[196:197], s[10:11], 0, v[162:163]
	s_mov_b32 m0, s56
	s_nop 0
	global_load_lds_dwordx4 v[196:197], off
	s_waitcnt lgkmcnt(8)
	s_barrier
	s_waitcnt lgkmcnt(0)
	s_setprio 1
	s_waitcnt lgkmcnt(0)
	v_mfma_f32_16x16x32_bf16 v[136:139], v[56:59], v[144:147], v[136:139]
	v_mfma_f32_16x16x32_bf16 v[140:143], v[72:75], v[144:147], v[140:143]
	v_mfma_f32_16x16x32_bf16 v[124:127], v[56:59], v[152:155], v[124:127]
	v_mfma_f32_16x16x32_bf16 v[120:123], v[72:75], v[152:155], v[120:123]
	v_mfma_f32_16x16x32_bf16 v[108:111], v[56:59], v[172:175], v[108:111]
	v_mfma_f32_16x16x32_bf16 v[104:107], v[72:75], v[172:175], v[104:107]
	v_mfma_f32_16x16x32_bf16 v[92:95], v[56:59], v[188:191], v[92:95]
	v_mfma_f32_16x16x32_bf16 v[88:91], v[72:75], v[188:191], v[88:91]
	v_mfma_f32_16x16x32_bf16 v[136:139], v[68:71], v[148:151], v[136:139]
	v_mfma_f32_16x16x32_bf16 v[140:143], v[76:79], v[148:151], v[140:143]
	v_mfma_f32_16x16x32_bf16 v[124:127], v[68:71], v[156:159], v[124:127]
	v_mfma_f32_16x16x32_bf16 v[120:123], v[76:79], v[156:159], v[120:123]
	v_mfma_f32_16x16x32_bf16 v[108:111], v[68:71], v[184:187], v[108:111]
	v_mfma_f32_16x16x32_bf16 v[104:107], v[76:79], v[184:187], v[104:107]
	v_mfma_f32_16x16x32_bf16 v[92:95], v[68:71], v[192:195], v[92:95]
	v_mfma_f32_16x16x32_bf16 v[88:91], v[76:79], v[192:195], v[88:91]
	s_setprio 0
	s_barrier
	s_add_i32 s10, 0, 0x1c000
	s_add_i32 s11, s17, s52
	v_add_u32_e32 v208, s10, v177
	v_lshl_add_u64 v[212:213], v[212:213], 0, s[36:37]
	s_mov_b32 m0, s11
	ds_read_b128 v[196:199], v208
	ds_read_b128 v[200:203], v208 offset:1024
	ds_read_b128 v[204:207], v208 offset:2048
	ds_read_b128 v[208:211], v208 offset:3072
	global_load_lds_dwordx4 v[212:213], off
	v_lshl_add_u64 v[212:213], v[214:215], 0, s[36:37]
	s_add_i32 m0, s11, 0x2000
	s_nop 0
	global_load_lds_dwordx4 v[212:213], off
	s_barrier
	s_waitcnt lgkmcnt(0)
	s_setprio 1
	s_waitcnt lgkmcnt(0)
	v_mfma_f32_16x16x32_bf16 v[132:135], v[196:199], v[144:147], v[132:135]
	v_mfma_f32_16x16x32_bf16 v[128:131], v[204:207], v[144:147], v[128:131]
	v_mfma_f32_16x16x32_bf16 v[116:119], v[196:199], v[152:155], v[116:119]
	v_mfma_f32_16x16x32_bf16 v[112:115], v[204:207], v[152:155], v[112:115]
	v_mfma_f32_16x16x32_bf16 v[100:103], v[196:199], v[172:175], v[100:103]
	v_mfma_f32_16x16x32_bf16 v[96:99], v[204:207], v[172:175], v[96:99]
	v_mfma_f32_16x16x32_bf16 v[84:87], v[196:199], v[188:191], v[84:87]
	v_mfma_f32_16x16x32_bf16 v[80:83], v[204:207], v[188:191], v[80:83]
	v_mfma_f32_16x16x32_bf16 v[132:135], v[200:203], v[148:151], v[132:135]
	v_mfma_f32_16x16x32_bf16 v[128:131], v[208:211], v[148:151], v[128:131]
	v_mfma_f32_16x16x32_bf16 v[116:119], v[200:203], v[156:159], v[116:119]
	v_mfma_f32_16x16x32_bf16 v[112:115], v[208:211], v[156:159], v[112:115]
	v_mfma_f32_16x16x32_bf16 v[100:103], v[200:203], v[184:187], v[100:103]
	v_mfma_f32_16x16x32_bf16 v[96:99], v[208:211], v[184:187], v[96:99]
	v_mfma_f32_16x16x32_bf16 v[84:87], v[200:203], v[192:195], v[84:87]
	v_mfma_f32_16x16x32_bf16 v[80:83], v[208:211], v[192:195], v[80:83]
	s_setprio 0
	s_mov_b32 m0, s64
	v_lshl_add_u64 v[212:213], v[216:217], 0, s[36:37]
	s_barrier
	ds_read_b128 v[144:147], v182 offset:49152
	ds_read_b128 v[148:151], v182 offset:50176
	ds_read_b128 v[152:155], v182 offset:51200
	ds_read_b128 v[156:159], v182 offset:52224
	ds_read_b128 v[172:175], v182 offset:53248
	ds_read_b128 v[184:187], v182 offset:54272
	ds_read_b128 v[188:191], v182 offset:55296
	ds_read_b128 v[192:195], v182 offset:56320
	global_load_lds_dwordx4 v[212:213], off
	v_lshl_add_u64 v[212:213], v[218:219], 0, s[36:37]
	s_mov_b32 m0, s65
	s_nop 0
	global_load_lds_dwordx4 v[212:213], off
	s_barrier
	s_waitcnt lgkmcnt(0)
	s_setprio 1
	s_waitcnt lgkmcnt(0)
	v_mfma_f32_16x16x32_bf16 v[64:67], v[56:59], v[144:147], v[64:67]
	v_mfma_f32_16x16x32_bf16 v[60:63], v[72:75], v[144:147], v[60:63]
	v_mfma_f32_16x16x32_bf16 v[44:47], v[56:59], v[152:155], v[44:47]
	v_mfma_f32_16x16x32_bf16 v[40:43], v[72:75], v[152:155], v[40:43]
	v_mfma_f32_16x16x32_bf16 v[28:31], v[56:59], v[172:175], v[28:31]
	v_mfma_f32_16x16x32_bf16 v[24:27], v[72:75], v[172:175], v[24:27]
	v_mfma_f32_16x16x32_bf16 v[12:15], v[56:59], v[188:191], v[12:15]
	v_mfma_f32_16x16x32_bf16 v[8:11], v[72:75], v[188:191], v[8:11]
	v_mfma_f32_16x16x32_bf16 v[64:67], v[68:71], v[148:151], v[64:67]
	v_mfma_f32_16x16x32_bf16 v[60:63], v[76:79], v[148:151], v[60:63]
	v_mfma_f32_16x16x32_bf16 v[44:47], v[68:71], v[156:159], v[44:47]
	v_mfma_f32_16x16x32_bf16 v[40:43], v[76:79], v[156:159], v[40:43]
	v_mfma_f32_16x16x32_bf16 v[28:31], v[68:71], v[184:187], v[28:31]
	v_mfma_f32_16x16x32_bf16 v[24:27], v[76:79], v[184:187], v[24:27]
	v_mfma_f32_16x16x32_bf16 v[12:15], v[68:71], v[192:195], v[12:15]
	v_mfma_f32_16x16x32_bf16 v[8:11], v[76:79], v[192:195], v[8:11]
	s_setprio 0
	s_barrier
	s_add_u32 s8, s8, 0xb0080
	s_addc_u32 s9, s9, 0
	s_add_i32 s10, s10, s52
	v_lshl_add_u64 v[56:57], s[8:9], 0, v[160:161]
	s_mov_b32 m0, s10
	s_nop 0
	global_load_lds_dwordx4 v[56:57], off
	v_lshl_add_u64 v[56:57], s[8:9], 0, v[162:163]
	s_add_i32 m0, s10, 0x2000
	s_nop 0
	global_load_lds_dwordx4 v[56:57], off
	s_waitcnt vmcnt(6)
	s_barrier
	s_setprio 1
	v_mfma_f32_16x16x32_bf16 v[52:55], v[196:199], v[144:147], v[52:55]
	v_mfma_f32_16x16x32_bf16 v[48:51], v[204:207], v[144:147], v[48:51]
	v_mfma_f32_16x16x32_bf16 v[36:39], v[196:199], v[152:155], v[36:39]
	v_mfma_f32_16x16x32_bf16 v[32:35], v[204:207], v[152:155], v[32:35]
	v_mfma_f32_16x16x32_bf16 v[20:23], v[196:199], v[172:175], v[20:23]
	v_mfma_f32_16x16x32_bf16 v[16:19], v[204:207], v[172:175], v[16:19]
	v_mfma_f32_16x16x32_bf16 v[4:7], v[196:199], v[188:191], v[4:7]
	v_mfma_f32_16x16x32_bf16 v[0:3], v[204:207], v[188:191], v[0:3]
	v_mfma_f32_16x16x32_bf16 v[52:55], v[200:203], v[148:151], v[52:55]
	v_mfma_f32_16x16x32_bf16 v[48:51], v[208:211], v[148:151], v[48:51]
	v_mfma_f32_16x16x32_bf16 v[36:39], v[200:203], v[156:159], v[36:39]
	v_mfma_f32_16x16x32_bf16 v[32:35], v[208:211], v[156:159], v[32:35]
	v_mfma_f32_16x16x32_bf16 v[20:23], v[200:203], v[184:187], v[20:23]
	v_mfma_f32_16x16x32_bf16 v[16:19], v[208:211], v[184:187], v[16:19]
	v_mfma_f32_16x16x32_bf16 v[4:7], v[200:203], v[192:195], v[4:7]
	v_mfma_f32_16x16x32_bf16 v[0:3], v[208:211], v[192:195], v[0:3]
	s_setprio 0
	s_add_u32 s14, s14, 0x100
	s_addc_u32 s15, s15, 0
	s_cmp_lt_i32 s16, s62
	s_mov_b64 s[10:11], s[6:7]
	s_mov_b32 s8, s16
	s_barrier
	s_cbranch_scc0 .Lpeel_done_P11

.Lpeel_done_P11:
.LBB0_799:
	v_cndmask_b32_e64 v56, 0, 1, s[40:41]
	v_cmp_ne_u32_e64 s[6:7], 1, v56
	s_andn2_b64 vcc, exec, s[40:41]
	s_cbranch_vccnz .LBB0_801
	s_barrier
